# baseline (speedup 1.0000x reference)
; #define PG8_STAGE(bufoff, gbase, voff) do { _Pragma("unroll") for (int _i = 0; _i < 2; ++_i) \
;         __builtin_amdgcn_global_load_lds((const unsigned*)((const char*)(gbase) + (voff)[_i]), (PG8_LAS unsigned*)(lds + (bufoff) + ldsw + _i * 8192), 16, 0, 0); } while (0)
; #define PG8_LDA(dst, b, h) do { _Pragma("unroll") for (int m = 0; m < 4; ++m) _Pragma("unroll") for (int k = 0; k < 2; ++k) dst[m][k] = *(const PG8_LAS bf16x8*)(lds + PG8_SA(b, h) + aoff + m * 2048 + k * 1024); } while (0)
; #define PG8_LDB(dst, b, h) do { _Pragma("unroll") for (int n = 0; n < 2; ++n) _Pragma("unroll") for (int k = 0; k < 2; ++k) dst[n][k] = *(const PG8_LAS bf16x8*)(lds + PG8_SB(b, h) + boff + n * 2048 + k * 1024); } while (0)
; #define PG8_MMA(ai, bj, At, Bt) do { __builtin_amdgcn_s_setprio(1); _Pragma("unroll") for (int m = 0; m < 4; ++m) _Pragma("unroll") for (int n = 0; n < 2; ++n) _Pragma("unroll") for (int k = 0; k < 2; ++k) \
;         acc[ai][bj][m][n] = __builtin_amdgcn_mfma_f32_16x16x32_bf16(Bt[n][k], At[m][k], acc[ai][bj][m][n], 0, 0, 0); __builtin_amdgcn_s_setprio(0); } while (0)
; #define PG8_WAIT_V(n) asm volatile("s_waitcnt vmcnt(" #n ")" ::: "memory")
; #define PG8_WAIT_L(n) asm volatile("s_waitcnt lgkmcnt(" #n ")" ::: "memory")
; #define PG8_BAR __builtin_amdgcn_s_barrier()
; #define PG8_SCHED __builtin_amdgcn_sched_barrier(0)
; template <class Epi, class Sched, bool ALIGN_EPI = false, bool SP2 = false>
; __device__ __forceinline__ void gemm_phase(PG8_LAS unsigned char* lds, const Gemm g, const Sched& S, const Epi& E, const int wv) {
;     ...
;             PG8_LDB(B0, 0, 0); PG8_LDB(B1, 0, 1); PG8_SCHED; PG8_LDA(At, 0, 0); PG8_STAGE(PG8_SA(1, 1), a1 + hstep, voffA);
;             PG8_WAIT_V(8); PG8_WAIT_L(0); PG8_BAR; PG8_MMA(0, 0, At, B0); PG8_MMA(0, 1, At, B1); PG8_BAR; PG8_SCHED;
;             PG8_LDA(At, 0, 1); PG8_STAGE(PG8_SB(0, 0), b2, voffB); PG8_STAGE(PG8_SB(0, 1), b2 + hstep, voffB); PG8_STAGE(PG8_SA(0, 0), a2, voffA);
;             PG8_WAIT_V(8); PG8_WAIT_L(0); PG8_BAR; PG8_MMA(1, 0, At, B0); PG8_MMA(1, 1, At, B1); PG8_BAR; PG8_SCHED;
.LBB0_134:
	s_add_u32 s26, s24, 0xfffc0080
	s_addc_u32 s27, s25, -1
	s_add_i32 s51, 0, 0x10000
	s_cmp_eq_u32 s50, 12
	s_cselect_b32 s29, s17, s27
	s_cselect_b32 s28, s23, s26
	v_add_u32_e32 v0, s51, v183
	s_cselect_b32 s27, s15, s49
	s_cselect_b32 s26, s33, s48
	s_add_i32 s54, 0, 0x14000
	ds_read_b128 v[142:145], v0
	ds_read_b128 v[146:149], v0 offset:1024
	ds_read_b128 v[150:153], v0 offset:2048
	ds_read_b128 v[154:157], v0 offset:3072
	v_add_u32_e32 v0, s54, v183
	ds_read_b128 v[158:161], v0
	ds_read_b128 v[162:165], v0 offset:1024
	ds_read_b128 v[166:169], v0 offset:2048
	ds_read_b128 v[170:173], v0 offset:3072
	v_lshl_add_u64 v[208:209], s[24:25], 0, v[138:139]
	s_add_i32 m0, s39, 0xc000
	ds_read_b128 v[174:177], v186
	ds_read_b128 v[178:181], v186 offset:1024
	ds_read_b128 v[188:191], v186 offset:2048
	ds_read_b128 v[192:195], v186 offset:3072
	ds_read_b128 v[196:199], v186 offset:4096
	ds_read_b128 v[200:203], v186 offset:5120
	ds_read_b128 v[204:207], v186 offset:6144
	ds_read_b128 v[218:221], v186 offset:7168
	global_load_lds_dwordx4 v[208:209], off
	v_lshl_add_u64 v[208:209], s[24:25], 0, v[140:141]
	s_add_i32 m0, s39, 0xe000
	s_nop 0
	global_load_lds_dwordx4 v[208:209], off
	s_waitcnt vmcnt(8)
	s_waitcnt lgkmcnt(0)
	s_barrier
	s_setprio 1
	s_waitcnt lgkmcnt(0)
	v_mfma_f32_16x16x32_bf16 v[126:129], v[142:145], v[174:177], v[126:129]
	v_mfma_f32_16x16x32_bf16 v[122:125], v[150:153], v[174:177], v[122:125]
	v_mfma_f32_16x16x32_bf16 v[110:113], v[142:145], v[188:191], v[110:113]
	v_mfma_f32_16x16x32_bf16 v[106:109], v[150:153], v[188:191], v[106:109]
	v_mfma_f32_16x16x32_bf16 v[94:97], v[142:145], v[196:199], v[94:97]
	v_mfma_f32_16x16x32_bf16 v[90:93], v[150:153], v[196:199], v[90:93]
	v_mfma_f32_16x16x32_bf16 v[78:81], v[142:145], v[204:207], v[78:81]
	v_mfma_f32_16x16x32_bf16 v[74:77], v[150:153], v[204:207], v[74:77]
	v_mfma_f32_16x16x32_bf16 v[126:129], v[146:149], v[178:181], v[126:129]
	v_mfma_f32_16x16x32_bf16 v[122:125], v[154:157], v[178:181], v[122:125]
	v_mfma_f32_16x16x32_bf16 v[110:113], v[146:149], v[192:195], v[110:113]
	v_mfma_f32_16x16x32_bf16 v[106:109], v[154:157], v[192:195], v[106:109]
	v_mfma_f32_16x16x32_bf16 v[94:97], v[146:149], v[200:203], v[94:97]
	v_mfma_f32_16x16x32_bf16 v[90:93], v[154:157], v[200:203], v[90:93]
	v_mfma_f32_16x16x32_bf16 v[78:81], v[146:149], v[218:221], v[78:81]
	v_mfma_f32_16x16x32_bf16 v[74:77], v[154:157], v[218:221], v[74:77]
	s_setprio 0
	s_setprio 1
	v_mfma_f32_16x16x32_bf16 v[118:121], v[158:161], v[174:177], v[118:121]
	v_mfma_f32_16x16x32_bf16 v[114:117], v[166:169], v[174:177], v[114:117]
	v_mfma_f32_16x16x32_bf16 v[102:105], v[158:161], v[188:191], v[102:105]
	v_mfma_f32_16x16x32_bf16 v[98:101], v[166:169], v[188:191], v[98:101]
	v_mfma_f32_16x16x32_bf16 v[86:89], v[158:161], v[196:199], v[86:89]
	v_mfma_f32_16x16x32_bf16 v[82:85], v[166:169], v[196:199], v[82:85]
	v_mfma_f32_16x16x32_bf16 v[70:73], v[158:161], v[204:207], v[70:73]
	v_mfma_f32_16x16x32_bf16 v[66:69], v[166:169], v[204:207], v[66:69]
	v_mfma_f32_16x16x32_bf16 v[118:121], v[162:165], v[178:181], v[118:121]
	v_mfma_f32_16x16x32_bf16 v[114:117], v[170:173], v[178:181], v[114:117]
	v_mfma_f32_16x16x32_bf16 v[102:105], v[162:165], v[192:195], v[102:105]
	v_mfma_f32_16x16x32_bf16 v[98:101], v[170:173], v[192:195], v[98:101]
	v_mfma_f32_16x16x32_bf16 v[86:89], v[162:165], v[200:203], v[86:89]
	v_mfma_f32_16x16x32_bf16 v[82:85], v[170:173], v[200:203], v[82:85]
	v_mfma_f32_16x16x32_bf16 v[70:73], v[162:165], v[218:221], v[70:73]
	v_mfma_f32_16x16x32_bf16 v[66:69], v[170:173], v[218:221], v[66:69]
	s_setprio 0
	s_barrier
	s_add_i32 s51, s51, s35
	v_lshl_add_u64 v[208:209], s[26:27], 0, v[134:135]
	s_mov_b32 m0, s51
	ds_read_b128 v[174:177], v186 offset:16384
	ds_read_b128 v[178:181], v186 offset:17408
	ds_read_b128 v[188:191], v186 offset:18432
	ds_read_b128 v[192:195], v186 offset:19456
	ds_read_b128 v[196:199], v186 offset:20480
	ds_read_b128 v[200:203], v186 offset:21504
	ds_read_b128 v[204:207], v186 offset:22528
	ds_read_b128 v[218:221], v186 offset:23552
	global_load_lds_dwordx4 v[208:209], off
	s_add_i32 m0, s51, 0x2000
	s_add_u32 s52, s26, 0x40000
	v_lshl_add_u64 v[210:211], s[26:27], 0, v[130:131]
	s_addc_u32 s53, s27, 0
	s_add_i32 s51, s54, s35
	global_load_lds_dwordx4 v[210:211], off
	v_lshl_add_u64 v[212:213], s[52:53], 0, v[134:135]
	s_mov_b32 m0, s51
	v_lshl_add_u64 v[214:215], s[28:29], 0, v[132:133]
	global_load_lds_dwordx4 v[212:213], off
	v_lshl_add_u64 v[212:213], s[52:53], 0, v[130:131]
	s_add_i32 m0, s51, 0x2000
	s_nop 0
	global_load_lds_dwordx4 v[212:213], off
	v_lshl_add_u64 v[212:213], s[28:29], 0, v[136:137]
	s_mov_b32 m0, s39
	s_nop 0
	global_load_lds_dwordx4 v[212:213], off
	s_mov_b32 m0, s40
	s_nop 0
	global_load_lds_dwordx4 v[214:215], off
	s_waitcnt vmcnt(8)
	s_waitcnt lgkmcnt(0)
	s_barrier
; #define PG8_STAGE(bufoff, gbase, voff) do { _Pragma("unroll") for (int _i = 0; _i < 2; ++_i) \
;         __builtin_amdgcn_global_load_lds((const unsigned*)((const char*)(gbase) + (voff)[_i]), (PG8_LAS unsigned*)(lds + (bufoff) + ldsw + _i * 8192), 16, 0, 0); } while (0)
; #define PG8_LDA(dst, b, h) do { _Pragma("unroll") for (int m = 0; m < 4; ++m) _Pragma("unroll") for (int k = 0; k < 2; ++k) dst[m][k] = *(const PG8_LAS bf16x8*)(lds + PG8_SA(b, h) + aoff + m * 2048 + k * 1024); } while (0)
; #define PG8_LDB(dst, b, h) do { _Pragma("unroll") for (int n = 0; n < 2; ++n) _Pragma("unroll") for (int k = 0; k < 2; ++k) dst[n][k] = *(const PG8_LAS bf16x8*)(lds + PG8_SB(b, h) + boff + n * 2048 + k * 1024); } while (0)
; #define PG8_MMA(ai, bj, At, Bt) do { __builtin_amdgcn_s_setprio(1); _Pragma("unroll") for (int m = 0; m < 4; ++m) _Pragma("unroll") for (int n = 0; n < 2; ++n) _Pragma("unroll") for (int k = 0; k < 2; ++k) \
;         acc[ai][bj][m][n] = __builtin_amdgcn_mfma_f32_16x16x32_bf16(Bt[n][k], At[m][k], acc[ai][bj][m][n], 0, 0, 0); __builtin_amdgcn_s_setprio(0); } while (0)
; #define PG8_WAIT_V(n) asm volatile("s_waitcnt vmcnt(" #n ")" ::: "memory")
; #define PG8_WAIT_L(n) asm volatile("s_waitcnt lgkmcnt(" #n ")" ::: "memory")
; #define PG8_BAR __builtin_amdgcn_s_barrier()
; #define PG8_SCHED __builtin_amdgcn_sched_barrier(0)
; template <class Epi, class Sched, bool ALIGN_EPI = false, bool SP2 = false>
; __device__ __forceinline__ void gemm_phase(PG8_LAS unsigned char* lds, const Gemm g, const Sched& S, const Epi& E, const int wv) {
;     ...
;             PG8_WAIT_V(8); PG8_WAIT_L(0); PG8_BAR; PG8_MMA(1, 0, At, B0); PG8_MMA(1, 1, At, B1); PG8_BAR; PG8_SCHED;
;             PG8_LDB(B0, 1, 0); PG8_LDB(B1, 1, 1); PG8_SCHED; PG8_LDA(At, 1, 0); PG8_STAGE(PG8_SA(0, 1), a2 + hstep, voffA);
;             PG8_WAIT_V(8); PG8_WAIT_L(0); PG8_BAR; PG8_MMA(0, 0, At, B0); PG8_MMA(0, 1, At, B1); PG8_BAR; PG8_SCHED;
	s_setprio 1
	s_waitcnt lgkmcnt(0)
	v_mfma_f32_16x16x32_bf16 v[62:65], v[142:145], v[174:177], v[62:65]
	v_mfma_f32_16x16x32_bf16 v[58:61], v[150:153], v[174:177], v[58:61]
	v_mfma_f32_16x16x32_bf16 v[46:49], v[142:145], v[188:191], v[46:49]
	v_mfma_f32_16x16x32_bf16 v[42:45], v[150:153], v[188:191], v[42:45]
	v_mfma_f32_16x16x32_bf16 v[30:33], v[142:145], v[196:199], v[30:33]
	v_mfma_f32_16x16x32_bf16 v[26:29], v[150:153], v[196:199], v[26:29]
	v_mfma_f32_16x16x32_bf16 v[14:17], v[142:145], v[204:207], v[14:17]
	v_mfma_f32_16x16x32_bf16 v[10:13], v[150:153], v[204:207], v[10:13]
	v_mfma_f32_16x16x32_bf16 v[62:65], v[146:149], v[178:181], v[62:65]
	v_mfma_f32_16x16x32_bf16 v[58:61], v[154:157], v[178:181], v[58:61]
	v_mfma_f32_16x16x32_bf16 v[46:49], v[146:149], v[192:195], v[46:49]
	v_mfma_f32_16x16x32_bf16 v[42:45], v[154:157], v[192:195], v[42:45]
	v_mfma_f32_16x16x32_bf16 v[30:33], v[146:149], v[200:203], v[30:33]
	v_mfma_f32_16x16x32_bf16 v[26:29], v[154:157], v[200:203], v[26:29]
	v_mfma_f32_16x16x32_bf16 v[14:17], v[146:149], v[218:221], v[14:17]
	v_mfma_f32_16x16x32_bf16 v[10:13], v[154:157], v[218:221], v[10:13]
	s_setprio 0
	s_setprio 1
	v_mfma_f32_16x16x32_bf16 v[54:57], v[158:161], v[174:177], v[54:57]
	v_mfma_f32_16x16x32_bf16 v[50:53], v[166:169], v[174:177], v[50:53]
	v_mfma_f32_16x16x32_bf16 v[38:41], v[158:161], v[188:191], v[38:41]
	v_mfma_f32_16x16x32_bf16 v[34:37], v[166:169], v[188:191], v[34:37]
	v_mfma_f32_16x16x32_bf16 v[22:25], v[158:161], v[196:199], v[22:25]
	v_mfma_f32_16x16x32_bf16 v[18:21], v[166:169], v[196:199], v[18:21]
	v_mfma_f32_16x16x32_bf16 v[6:9], v[158:161], v[204:207], v[6:9]
	v_mfma_f32_16x16x32_bf16 v[2:5], v[166:169], v[204:207], v[2:5]
	v_mfma_f32_16x16x32_bf16 v[54:57], v[162:165], v[178:181], v[54:57]
	v_mfma_f32_16x16x32_bf16 v[50:53], v[170:173], v[178:181], v[50:53]
	v_mfma_f32_16x16x32_bf16 v[38:41], v[162:165], v[192:195], v[38:41]
	v_mfma_f32_16x16x32_bf16 v[34:37], v[170:173], v[192:195], v[34:37]
	v_mfma_f32_16x16x32_bf16 v[22:25], v[162:165], v[200:203], v[22:25]
	v_mfma_f32_16x16x32_bf16 v[18:21], v[170:173], v[200:203], v[18:21]
	v_mfma_f32_16x16x32_bf16 v[6:9], v[162:165], v[218:221], v[6:9]
	v_mfma_f32_16x16x32_bf16 v[2:5], v[170:173], v[218:221], v[2:5]
	s_setprio 0
	s_barrier
	s_add_i32 s51, 0, 0x18000
	v_add_u32_e32 v0, s51, v183
	s_add_i32 s52, 0, 0x1c000
	ds_read_b128 v[142:145], v0
	ds_read_b128 v[146:149], v0 offset:1024
	ds_read_b128 v[150:153], v0 offset:2048
	ds_read_b128 v[154:157], v0 offset:3072
	v_add_u32_e32 v0, s52, v183
	ds_read_b128 v[158:161], v0
	ds_read_b128 v[162:165], v0 offset:1024
	ds_read_b128 v[166:169], v0 offset:2048
	ds_read_b128 v[170:173], v0 offset:3072
	s_add_u32 s28, s28, 0x40000
	s_addc_u32 s29, s29, 0
	s_mov_b32 m0, s41
	v_lshl_add_u64 v[216:217], s[28:29], 0, v[136:137]
	ds_read_b128 v[174:177], v186 offset:32768
	ds_read_b128 v[178:181], v186 offset:33792
	ds_read_b128 v[188:191], v186 offset:34816
	ds_read_b128 v[192:195], v186 offset:35840
	ds_read_b128 v[196:199], v186 offset:36864
	ds_read_b128 v[200:203], v186 offset:37888
	ds_read_b128 v[204:207], v186 offset:38912
	ds_read_b128 v[218:221], v186 offset:39936
	global_load_lds_dwordx4 v[216:217], off
	v_lshl_add_u64 v[216:217], s[28:29], 0, v[132:133]
	s_mov_b32 m0, s42
	s_nop 0
	global_load_lds_dwordx4 v[216:217], off
	s_waitcnt vmcnt(8)
	s_waitcnt lgkmcnt(0)
	s_barrier
	s_setprio 1
	s_waitcnt lgkmcnt(0)
	v_mfma_f32_16x16x32_bf16 v[126:129], v[142:145], v[174:177], v[126:129]
	v_mfma_f32_16x16x32_bf16 v[122:125], v[150:153], v[174:177], v[122:125]
	v_mfma_f32_16x16x32_bf16 v[110:113], v[142:145], v[188:191], v[110:113]
	v_mfma_f32_16x16x32_bf16 v[106:109], v[150:153], v[188:191], v[106:109]
	v_mfma_f32_16x16x32_bf16 v[94:97], v[142:145], v[196:199], v[94:97]
	v_mfma_f32_16x16x32_bf16 v[90:93], v[150:153], v[196:199], v[90:93]
	v_mfma_f32_16x16x32_bf16 v[78:81], v[142:145], v[204:207], v[78:81]
	v_mfma_f32_16x16x32_bf16 v[74:77], v[150:153], v[204:207], v[74:77]
	v_mfma_f32_16x16x32_bf16 v[126:129], v[146:149], v[178:181], v[126:129]
	v_mfma_f32_16x16x32_bf16 v[122:125], v[154:157], v[178:181], v[122:125]
	v_mfma_f32_16x16x32_bf16 v[110:113], v[146:149], v[192:195], v[110:113]
	v_mfma_f32_16x16x32_bf16 v[106:109], v[154:157], v[192:195], v[106:109]
	v_mfma_f32_16x16x32_bf16 v[94:97], v[146:149], v[200:203], v[94:97]
	v_mfma_f32_16x16x32_bf16 v[90:93], v[154:157], v[200:203], v[90:93]
	v_mfma_f32_16x16x32_bf16 v[78:81], v[146:149], v[218:221], v[78:81]
	v_mfma_f32_16x16x32_bf16 v[74:77], v[154:157], v[218:221], v[74:77]
	s_setprio 0
	s_setprio 1
	v_mfma_f32_16x16x32_bf16 v[118:121], v[158:161], v[174:177], v[118:121]
	v_mfma_f32_16x16x32_bf16 v[114:117], v[166:169], v[174:177], v[114:117]
	v_mfma_f32_16x16x32_bf16 v[102:105], v[158:161], v[188:191], v[102:105]
	v_mfma_f32_16x16x32_bf16 v[98:101], v[166:169], v[188:191], v[98:101]
	v_mfma_f32_16x16x32_bf16 v[86:89], v[158:161], v[196:199], v[86:89]
	v_mfma_f32_16x16x32_bf16 v[82:85], v[166:169], v[196:199], v[82:85]
	v_mfma_f32_16x16x32_bf16 v[70:73], v[158:161], v[204:207], v[70:73]
	v_mfma_f32_16x16x32_bf16 v[66:69], v[166:169], v[204:207], v[66:69]
	v_mfma_f32_16x16x32_bf16 v[118:121], v[162:165], v[178:181], v[118:121]
	v_mfma_f32_16x16x32_bf16 v[114:117], v[170:173], v[178:181], v[114:117]
	v_mfma_f32_16x16x32_bf16 v[102:105], v[162:165], v[192:195], v[102:105]
	v_mfma_f32_16x16x32_bf16 v[98:101], v[170:173], v[192:195], v[98:101]
	v_mfma_f32_16x16x32_bf16 v[86:89], v[162:165], v[200:203], v[86:89]
	v_mfma_f32_16x16x32_bf16 v[82:85], v[170:173], v[200:203], v[82:85]
	v_mfma_f32_16x16x32_bf16 v[70:73], v[162:165], v[218:221], v[70:73]
	v_mfma_f32_16x16x32_bf16 v[66:69], v[170:173], v[218:221], v[66:69]
	s_setprio 0
	s_barrier
; #define PG8_STAGE(bufoff, gbase, voff) do { _Pragma("unroll") for (int _i = 0; _i < 2; ++_i) \
;         __builtin_amdgcn_global_load_lds((const unsigned*)((const char*)(gbase) + (voff)[_i]), (PG8_LAS unsigned*)(lds + (bufoff) + ldsw + _i * 8192), 16, 0, 0); } while (0)
; #define PG8_LDA(dst, b, h) do { _Pragma("unroll") for (int m = 0; m < 4; ++m) _Pragma("unroll") for (int k = 0; k < 2; ++k) dst[m][k] = *(const PG8_LAS bf16x8*)(lds + PG8_SA(b, h) + aoff + m * 2048 + k * 1024); } while (0)
; #define PG8_MMA(ai, bj, At, Bt) do { __builtin_amdgcn_s_setprio(1); _Pragma("unroll") for (int m = 0; m < 4; ++m) _Pragma("unroll") for (int n = 0; n < 2; ++n) _Pragma("unroll") for (int k = 0; k < 2; ++k) \
;         acc[ai][bj][m][n] = __builtin_amdgcn_mfma_f32_16x16x32_bf16(Bt[n][k], At[m][k], acc[ai][bj][m][n], 0, 0, 0); __builtin_amdgcn_s_setprio(0); } while (0)
; #define PG8_WAIT_V(n) asm volatile("s_waitcnt vmcnt(" #n ")" ::: "memory")
; #define PG8_WAIT_L(n) asm volatile("s_waitcnt lgkmcnt(" #n ")" ::: "memory")
; #define PG8_BAR __builtin_amdgcn_s_barrier()
; #define PG8_SCHED __builtin_amdgcn_sched_barrier(0)
; template <class Epi, class Sched, bool ALIGN_EPI = false, bool SP2 = false>
; __device__ __forceinline__ void gemm_phase(PG8_LAS unsigned char* lds, const Gemm g, const Sched& S, const Epi& E, const int wv) {
;     ...
;         for (int t = 0; t < nt; t += 2) {
;             const bool last = (t == nt - 2);
;     ...
;             PG8_LDA(At, 1, 1); PG8_STAGE(PG8_SB(1, 0), b3, voffB); PG8_STAGE(PG8_SB(1, 1), b3 + hstep, voffB); PG8_STAGE(PG8_SA(1, 0), a3, voffA);
;             PG8_WAIT_V(8); PG8_WAIT_L(0); PG8_BAR; PG8_MMA(1, 0, At, B0); PG8_MMA(1, 1, At, B1); PG8_BAR; PG8_SCHED;
	s_add_i32 s28, s51, s35
	v_lshl_add_u64 v[208:209], v[208:209], 0, s[2:3]
	s_mov_b32 m0, s28
	ds_read_b128 v[174:177], v186 offset:49152
	ds_read_b128 v[178:181], v186 offset:50176
	ds_read_b128 v[188:191], v186 offset:51200
	ds_read_b128 v[192:195], v186 offset:52224
	ds_read_b128 v[196:199], v186 offset:53248
	ds_read_b128 v[200:203], v186 offset:54272
	ds_read_b128 v[204:207], v186 offset:55296
	ds_read_b128 v[218:221], v186 offset:56320
	global_load_lds_dwordx4 v[208:209], off
	s_add_i32 m0, s28, 0x2000
	s_add_u32 s26, s26, 0x40080
	v_lshl_add_u64 v[208:209], v[210:211], 0, s[2:3]
	s_addc_u32 s27, s27, 0
	s_add_i32 s28, s52, s35
	global_load_lds_dwordx4 v[208:209], off
	v_lshl_add_u64 v[208:209], s[26:27], 0, v[134:135]
	s_mov_b32 m0, s28
	s_nop 0
	global_load_lds_dwordx4 v[208:209], off
	v_lshl_add_u64 v[208:209], s[26:27], 0, v[130:131]
	s_add_i32 m0, s28, 0x2000
	s_nop 0
	global_load_lds_dwordx4 v[208:209], off
	v_lshl_add_u64 v[208:209], v[212:213], 0, s[2:3]
	s_mov_b32 m0, s44
	s_nop 0
	global_load_lds_dwordx4 v[208:209], off
	v_lshl_add_u64 v[208:209], v[214:215], 0, s[2:3]
	s_mov_b32 m0, s45
	s_nop 0
	global_load_lds_dwordx4 v[208:209], off
	s_waitcnt vmcnt(8)
	s_waitcnt lgkmcnt(0)
	s_barrier
	s_setprio 1
	s_waitcnt lgkmcnt(0)
	v_mfma_f32_16x16x32_bf16 v[62:65], v[142:145], v[174:177], v[62:65]
	v_mfma_f32_16x16x32_bf16 v[58:61], v[150:153], v[174:177], v[58:61]
	v_mfma_f32_16x16x32_bf16 v[46:49], v[142:145], v[188:191], v[46:49]
	v_mfma_f32_16x16x32_bf16 v[42:45], v[150:153], v[188:191], v[42:45]
	v_mfma_f32_16x16x32_bf16 v[30:33], v[142:145], v[196:199], v[30:33]
	v_mfma_f32_16x16x32_bf16 v[26:29], v[150:153], v[196:199], v[26:29]
	v_mfma_f32_16x16x32_bf16 v[14:17], v[142:145], v[204:207], v[14:17]
	v_mfma_f32_16x16x32_bf16 v[10:13], v[150:153], v[204:207], v[10:13]
	v_mfma_f32_16x16x32_bf16 v[62:65], v[146:149], v[178:181], v[62:65]
	v_mfma_f32_16x16x32_bf16 v[58:61], v[154:157], v[178:181], v[58:61]
	v_mfma_f32_16x16x32_bf16 v[46:49], v[146:149], v[192:195], v[46:49]
	v_mfma_f32_16x16x32_bf16 v[42:45], v[154:157], v[192:195], v[42:45]
	v_mfma_f32_16x16x32_bf16 v[30:33], v[146:149], v[200:203], v[30:33]
	v_mfma_f32_16x16x32_bf16 v[26:29], v[154:157], v[200:203], v[26:29]
	v_mfma_f32_16x16x32_bf16 v[14:17], v[146:149], v[218:221], v[14:17]
	v_mfma_f32_16x16x32_bf16 v[10:13], v[154:157], v[218:221], v[10:13]
	s_setprio 0
	s_setprio 1
	v_mfma_f32_16x16x32_bf16 v[54:57], v[158:161], v[174:177], v[54:57]
	v_mfma_f32_16x16x32_bf16 v[50:53], v[166:169], v[174:177], v[50:53]
	v_mfma_f32_16x16x32_bf16 v[38:41], v[158:161], v[188:191], v[38:41]
	v_mfma_f32_16x16x32_bf16 v[34:37], v[166:169], v[188:191], v[34:37]
	v_mfma_f32_16x16x32_bf16 v[22:25], v[158:161], v[196:199], v[22:25]
	v_mfma_f32_16x16x32_bf16 v[18:21], v[166:169], v[196:199], v[18:21]
	v_mfma_f32_16x16x32_bf16 v[6:9], v[158:161], v[204:207], v[6:9]
	v_mfma_f32_16x16x32_bf16 v[2:5], v[166:169], v[204:207], v[2:5]
	v_mfma_f32_16x16x32_bf16 v[54:57], v[162:165], v[178:181], v[54:57]
	v_mfma_f32_16x16x32_bf16 v[50:53], v[170:173], v[178:181], v[50:53]
	v_mfma_f32_16x16x32_bf16 v[38:41], v[162:165], v[192:195], v[38:41]
	v_mfma_f32_16x16x32_bf16 v[34:37], v[170:173], v[192:195], v[34:37]
	v_mfma_f32_16x16x32_bf16 v[22:25], v[162:165], v[200:203], v[22:25]
	v_mfma_f32_16x16x32_bf16 v[18:21], v[170:173], v[200:203], v[18:21]
	v_mfma_f32_16x16x32_bf16 v[6:9], v[162:165], v[218:221], v[6:9]
	v_mfma_f32_16x16x32_bf16 v[2:5], v[170:173], v[218:221], v[2:5]
	s_setprio 0
	s_add_i32 s50, s50, 2
	s_add_u32 s24, s24, 0x100
	s_addc_u32 s25, s25, 0
	s_add_u32 s48, s48, 0x100
	s_addc_u32 s49, s49, 0
	s_cmp_gt_u32 s50, 13
	s_barrier
	s_cbranch_scc0 .LBB0_134
	s_and_b64 vcc, exec, s[10:11]
	s_cbranch_vccz .LBB0_137
	s_barrier

; #define PG8_STAGE(bufoff, gbase, voff) do { _Pragma("unroll") for (int _i = 0; _i < 2; ++_i) \
;         __builtin_amdgcn_global_load_lds((const unsigned*)((const char*)(gbase) + (voff)[_i]), (PG8_LAS unsigned*)(lds + (bufoff) + ldsw + _i * 8192), 16, 0, 0); } while (0)
; #define PG8_LDA(dst, b, h) do { _Pragma("unroll") for (int m = 0; m < 4; ++m) _Pragma("unroll") for (int k = 0; k < 2; ++k) dst[m][k] = *(const PG8_LAS bf16x8*)(lds + PG8_SA(b, h) + aoff + m * 2048 + k * 1024); } while (0)
; #define PG8_LDB(dst, b, h) do { _Pragma("unroll") for (int n = 0; n < 2; ++n) _Pragma("unroll") for (int k = 0; k < 2; ++k) dst[n][k] = *(const PG8_LAS bf16x8*)(lds + PG8_SB(b, h) + boff + n * 2048 + k * 1024); } while (0)
; #define PG8_MMA(ai, bj, At, Bt) do { __builtin_amdgcn_s_setprio(1); _Pragma("unroll") for (int m = 0; m < 4; ++m) _Pragma("unroll") for (int n = 0; n < 2; ++n) _Pragma("unroll") for (int k = 0; k < 2; ++k) \
;         acc[ai][bj][m][n] = __builtin_amdgcn_mfma_f32_16x16x32_bf16(Bt[n][k], At[m][k], acc[ai][bj][m][n], 0, 0, 0); __builtin_amdgcn_s_setprio(0); } while (0)
; #define PG8_WAIT_V(n) asm volatile("s_waitcnt vmcnt(" #n ")" ::: "memory")
; #define PG8_WAIT_L(n) asm volatile("s_waitcnt lgkmcnt(" #n ")" ::: "memory")
; #define PG8_BAR __builtin_amdgcn_s_barrier()
; #define PG8_SCHED __builtin_amdgcn_sched_barrier(0)
; template <class Epi, class Sched, bool ALIGN_EPI = false, bool SP2 = false>
; __device__ __forceinline__ void gemm_phase(PG8_LAS unsigned char* lds, const Gemm g, const Sched& S, const Epi& E, const int wv) {
;     ...
;             PG8_LDB(B0, 0, 0); PG8_LDB(B1, 0, 1); PG8_SCHED; PG8_LDA(At, 0, 0); PG8_STAGE(PG8_SA(1, 1), a1 + hstep, voffA);
;             PG8_WAIT_V(8); PG8_WAIT_L(0); PG8_BAR; PG8_MMA(0, 0, At, B0); PG8_MMA(0, 1, At, B1); PG8_BAR; PG8_SCHED;
;             PG8_LDA(At, 0, 1); PG8_STAGE(PG8_SB(0, 0), b2, voffB); PG8_STAGE(PG8_SB(0, 1), b2 + hstep, voffB); PG8_STAGE(PG8_SA(0, 0), a2, voffA);
;             PG8_WAIT_V(8); PG8_WAIT_L(0); PG8_BAR; PG8_MMA(1, 0, At, B0); PG8_MMA(1, 1, At, B1); PG8_BAR; PG8_SCHED;
.LBB0_156:
	s_add_u32 s20, s18, 0xfffc0080
	s_addc_u32 s21, s19, -1
	s_add_i32 s45, 0, 0x10000
	s_cmp_eq_u32 s44, 12
	s_cselect_b32 s23, s11, s21
	s_cselect_b32 s22, s40, s20
	v_add_u32_e32 v152, s45, v155
	s_cselect_b32 s21, s9, s43
	s_cselect_b32 s20, s41, s42
	s_add_i32 s48, 0, 0x14000
	ds_read_b128 v[140:143], v152
	ds_read_b128 v[144:147], v152 offset:1024
	ds_read_b128 v[148:151], v152 offset:2048
	ds_read_b128 v[158:161], v152 offset:3072
	v_add_u32_e32 v152, s48, v155
	ds_read_b128 v[162:165], v152
	ds_read_b128 v[166:169], v152 offset:1024
	ds_read_b128 v[170:173], v152 offset:2048
	ds_read_b128 v[174:177], v152 offset:3072
	v_lshl_add_u64 v[152:153], s[18:19], 0, v[136:137]
	s_add_i32 m0, s17, 0xc000
	ds_read_b128 v[178:181], v157
	ds_read_b128 v[182:185], v157 offset:1024
	ds_read_b128 v[186:189], v157 offset:2048
	ds_read_b128 v[190:193], v157 offset:3072
	ds_read_b128 v[194:197], v157 offset:4096
	ds_read_b128 v[198:201], v157 offset:5120
	ds_read_b128 v[202:205], v157 offset:6144
	ds_read_b128 v[206:209], v157 offset:7168
	global_load_lds_dwordx4 v[152:153], off
	v_lshl_add_u64 v[152:153], s[18:19], 0, v[138:139]
	s_add_i32 m0, s17, 0xe000
	s_nop 0
	global_load_lds_dwordx4 v[152:153], off
	s_waitcnt vmcnt(8)
	s_waitcnt lgkmcnt(0)
	s_barrier
	s_setprio 1
	s_waitcnt lgkmcnt(0)
	v_mfma_f32_16x16x32_bf16 v[126:129], v[140:143], v[178:181], v[126:129]
	v_mfma_f32_16x16x32_bf16 v[122:125], v[148:151], v[178:181], v[122:125]
	v_mfma_f32_16x16x32_bf16 v[118:121], v[140:143], v[186:189], v[118:121]
	v_mfma_f32_16x16x32_bf16 v[114:117], v[148:151], v[186:189], v[114:117]
	v_mfma_f32_16x16x32_bf16 v[98:101], v[140:143], v[194:197], v[98:101]
	v_mfma_f32_16x16x32_bf16 v[90:93], v[148:151], v[194:197], v[90:93]
	v_mfma_f32_16x16x32_bf16 v[78:81], v[140:143], v[202:205], v[78:81]
	v_mfma_f32_16x16x32_bf16 v[74:77], v[148:151], v[202:205], v[74:77]
	v_mfma_f32_16x16x32_bf16 v[126:129], v[144:147], v[182:185], v[126:129]
	v_mfma_f32_16x16x32_bf16 v[122:125], v[158:161], v[182:185], v[122:125]
	v_mfma_f32_16x16x32_bf16 v[118:121], v[144:147], v[190:193], v[118:121]
	v_mfma_f32_16x16x32_bf16 v[114:117], v[158:161], v[190:193], v[114:117]
	v_mfma_f32_16x16x32_bf16 v[98:101], v[144:147], v[198:201], v[98:101]
	v_mfma_f32_16x16x32_bf16 v[90:93], v[158:161], v[198:201], v[90:93]
	v_mfma_f32_16x16x32_bf16 v[78:81], v[144:147], v[206:209], v[78:81]
	v_mfma_f32_16x16x32_bf16 v[74:77], v[158:161], v[206:209], v[74:77]
	s_setprio 0
	s_setprio 1
	v_mfma_f32_16x16x32_bf16 v[110:113], v[162:165], v[178:181], v[110:113]
	v_mfma_f32_16x16x32_bf16 v[106:109], v[170:173], v[178:181], v[106:109]
	v_mfma_f32_16x16x32_bf16 v[102:105], v[162:165], v[186:189], v[102:105]
	v_mfma_f32_16x16x32_bf16 v[94:97], v[170:173], v[186:189], v[94:97]
	v_mfma_f32_16x16x32_bf16 v[86:89], v[162:165], v[194:197], v[86:89]
	v_mfma_f32_16x16x32_bf16 v[82:85], v[170:173], v[194:197], v[82:85]
	v_mfma_f32_16x16x32_bf16 v[70:73], v[162:165], v[202:205], v[70:73]
	v_mfma_f32_16x16x32_bf16 v[66:69], v[170:173], v[202:205], v[66:69]
	v_mfma_f32_16x16x32_bf16 v[110:113], v[166:169], v[182:185], v[110:113]
	v_mfma_f32_16x16x32_bf16 v[106:109], v[174:177], v[182:185], v[106:109]
	v_mfma_f32_16x16x32_bf16 v[102:105], v[166:169], v[190:193], v[102:105]
	v_mfma_f32_16x16x32_bf16 v[94:97], v[174:177], v[190:193], v[94:97]
	v_mfma_f32_16x16x32_bf16 v[86:89], v[166:169], v[198:201], v[86:89]
	v_mfma_f32_16x16x32_bf16 v[82:85], v[174:177], v[198:201], v[82:85]
	v_mfma_f32_16x16x32_bf16 v[70:73], v[166:169], v[206:209], v[70:73]
	v_mfma_f32_16x16x32_bf16 v[66:69], v[174:177], v[206:209], v[66:69]
	s_setprio 0
	s_barrier
	s_add_i32 s45, s45, s24
	v_lshl_add_u64 v[152:153], s[20:21], 0, v[0:1]
	s_mov_b32 m0, s45
	ds_read_b128 v[178:181], v157 offset:16384
	ds_read_b128 v[182:185], v157 offset:17408
	ds_read_b128 v[186:189], v157 offset:18432
	ds_read_b128 v[190:193], v157 offset:19456
	ds_read_b128 v[194:197], v157 offset:20480
	ds_read_b128 v[198:201], v157 offset:21504
	ds_read_b128 v[202:205], v157 offset:22528
	ds_read_b128 v[206:209], v157 offset:23552
	global_load_lds_dwordx4 v[152:153], off
	s_add_i32 m0, s45, 0x2000
	s_add_u32 s46, s20, 0x40000
	v_lshl_add_u64 v[210:211], s[20:21], 0, v[130:131]
	s_addc_u32 s47, s21, 0
	s_add_i32 s45, s48, s24
	global_load_lds_dwordx4 v[210:211], off
	v_lshl_add_u64 v[212:213], s[46:47], 0, v[0:1]
	s_mov_b32 m0, s45
	v_lshl_add_u64 v[214:215], s[22:23], 0, v[132:133]
	global_load_lds_dwordx4 v[212:213], off
	v_lshl_add_u64 v[212:213], s[46:47], 0, v[130:131]
	s_add_i32 m0, s45, 0x2000
	s_nop 0
	global_load_lds_dwordx4 v[212:213], off
	v_lshl_add_u64 v[212:213], s[22:23], 0, v[134:135]
	s_mov_b32 m0, s17
	s_nop 0
	global_load_lds_dwordx4 v[212:213], off
	s_mov_b32 m0, s26
	s_nop 0
	global_load_lds_dwordx4 v[214:215], off
	s_waitcnt vmcnt(8)
	s_waitcnt lgkmcnt(0)
	s_barrier
; #define PG8_STAGE(bufoff, gbase, voff) do { _Pragma("unroll") for (int _i = 0; _i < 2; ++_i) \
;         __builtin_amdgcn_global_load_lds((const unsigned*)((const char*)(gbase) + (voff)[_i]), (PG8_LAS unsigned*)(lds + (bufoff) + ldsw + _i * 8192), 16, 0, 0); } while (0)
; #define PG8_LDA(dst, b, h) do { _Pragma("unroll") for (int m = 0; m < 4; ++m) _Pragma("unroll") for (int k = 0; k < 2; ++k) dst[m][k] = *(const PG8_LAS bf16x8*)(lds + PG8_SA(b, h) + aoff + m * 2048 + k * 1024); } while (0)
; #define PG8_LDB(dst, b, h) do { _Pragma("unroll") for (int n = 0; n < 2; ++n) _Pragma("unroll") for (int k = 0; k < 2; ++k) dst[n][k] = *(const PG8_LAS bf16x8*)(lds + PG8_SB(b, h) + boff + n * 2048 + k * 1024); } while (0)
; #define PG8_MMA(ai, bj, At, Bt) do { __builtin_amdgcn_s_setprio(1); _Pragma("unroll") for (int m = 0; m < 4; ++m) _Pragma("unroll") for (int n = 0; n < 2; ++n) _Pragma("unroll") for (int k = 0; k < 2; ++k) \
;         acc[ai][bj][m][n] = __builtin_amdgcn_mfma_f32_16x16x32_bf16(Bt[n][k], At[m][k], acc[ai][bj][m][n], 0, 0, 0); __builtin_amdgcn_s_setprio(0); } while (0)
; #define PG8_WAIT_V(n) asm volatile("s_waitcnt vmcnt(" #n ")" ::: "memory")
; #define PG8_WAIT_L(n) asm volatile("s_waitcnt lgkmcnt(" #n ")" ::: "memory")
; #define PG8_BAR __builtin_amdgcn_s_barrier()
; #define PG8_SCHED __builtin_amdgcn_sched_barrier(0)
; template <class Epi, class Sched, bool ALIGN_EPI = false, bool SP2 = false>
; __device__ __forceinline__ void gemm_phase(PG8_LAS unsigned char* lds, const Gemm g, const Sched& S, const Epi& E, const int wv) {
;     ...
;             PG8_WAIT_V(8); PG8_WAIT_L(0); PG8_BAR; PG8_MMA(1, 0, At, B0); PG8_MMA(1, 1, At, B1); PG8_BAR; PG8_SCHED;
;             PG8_LDB(B0, 1, 0); PG8_LDB(B1, 1, 1); PG8_SCHED; PG8_LDA(At, 1, 0); PG8_STAGE(PG8_SA(0, 1), a2 + hstep, voffA);
;             PG8_WAIT_V(8); PG8_WAIT_L(0); PG8_BAR; PG8_MMA(0, 0, At, B0); PG8_MMA(0, 1, At, B1); PG8_BAR; PG8_SCHED;
	s_setprio 1
	s_waitcnt lgkmcnt(0)
	v_mfma_f32_16x16x32_bf16 v[62:65], v[140:143], v[178:181], v[62:65]
	v_mfma_f32_16x16x32_bf16 v[58:61], v[148:151], v[178:181], v[58:61]
	v_mfma_f32_16x16x32_bf16 v[46:49], v[140:143], v[186:189], v[46:49]
	v_mfma_f32_16x16x32_bf16 v[42:45], v[148:151], v[186:189], v[42:45]
	v_mfma_f32_16x16x32_bf16 v[30:33], v[140:143], v[194:197], v[30:33]
	v_mfma_f32_16x16x32_bf16 v[26:29], v[148:151], v[194:197], v[26:29]
	v_mfma_f32_16x16x32_bf16 v[14:17], v[140:143], v[202:205], v[14:17]
	v_mfma_f32_16x16x32_bf16 v[10:13], v[148:151], v[202:205], v[10:13]
	v_mfma_f32_16x16x32_bf16 v[62:65], v[144:147], v[182:185], v[62:65]
	v_mfma_f32_16x16x32_bf16 v[58:61], v[158:161], v[182:185], v[58:61]
	v_mfma_f32_16x16x32_bf16 v[46:49], v[144:147], v[190:193], v[46:49]
	v_mfma_f32_16x16x32_bf16 v[42:45], v[158:161], v[190:193], v[42:45]
	v_mfma_f32_16x16x32_bf16 v[30:33], v[144:147], v[198:201], v[30:33]
	v_mfma_f32_16x16x32_bf16 v[26:29], v[158:161], v[198:201], v[26:29]
	v_mfma_f32_16x16x32_bf16 v[14:17], v[144:147], v[206:209], v[14:17]
	v_mfma_f32_16x16x32_bf16 v[10:13], v[158:161], v[206:209], v[10:13]
	s_setprio 0
	s_setprio 1
	v_mfma_f32_16x16x32_bf16 v[54:57], v[162:165], v[178:181], v[54:57]
	v_mfma_f32_16x16x32_bf16 v[50:53], v[170:173], v[178:181], v[50:53]
	v_mfma_f32_16x16x32_bf16 v[38:41], v[162:165], v[186:189], v[38:41]
	v_mfma_f32_16x16x32_bf16 v[34:37], v[170:173], v[186:189], v[34:37]
	v_mfma_f32_16x16x32_bf16 v[22:25], v[162:165], v[194:197], v[22:25]
	v_mfma_f32_16x16x32_bf16 v[18:21], v[170:173], v[194:197], v[18:21]
	v_mfma_f32_16x16x32_bf16 v[6:9], v[162:165], v[202:205], v[6:9]
	v_mfma_f32_16x16x32_bf16 v[2:5], v[170:173], v[202:205], v[2:5]
	v_mfma_f32_16x16x32_bf16 v[54:57], v[166:169], v[182:185], v[54:57]
	v_mfma_f32_16x16x32_bf16 v[50:53], v[174:177], v[182:185], v[50:53]
	v_mfma_f32_16x16x32_bf16 v[38:41], v[166:169], v[190:193], v[38:41]
	v_mfma_f32_16x16x32_bf16 v[34:37], v[174:177], v[190:193], v[34:37]
	v_mfma_f32_16x16x32_bf16 v[22:25], v[166:169], v[198:201], v[22:25]
	v_mfma_f32_16x16x32_bf16 v[18:21], v[174:177], v[198:201], v[18:21]
	v_mfma_f32_16x16x32_bf16 v[6:9], v[166:169], v[206:209], v[6:9]
	v_mfma_f32_16x16x32_bf16 v[2:5], v[174:177], v[206:209], v[2:5]
	s_setprio 0
	s_barrier
	s_add_i32 s45, 0, 0x18000
	s_add_i32 s46, 0, 0x1c000
	v_add_u32_e32 v158, s45, v155
	v_add_u32_e32 v174, s46, v155
	ds_read_b128 v[140:143], v158
	ds_read_b128 v[144:147], v158 offset:1024
	ds_read_b128 v[148:151], v158 offset:2048
	ds_read_b128 v[158:161], v158 offset:3072
	ds_read_b128 v[162:165], v174
	ds_read_b128 v[166:169], v174 offset:1024
	ds_read_b128 v[170:173], v174 offset:2048
	ds_read_b128 v[174:177], v174 offset:3072
	s_add_u32 s22, s22, 0x40000
	s_addc_u32 s23, s23, 0
	s_mov_b32 m0, s27
	v_lshl_add_u64 v[216:217], s[22:23], 0, v[134:135]
	ds_read_b128 v[178:181], v157 offset:32768
	ds_read_b128 v[182:185], v157 offset:33792
	ds_read_b128 v[186:189], v157 offset:34816
	ds_read_b128 v[190:193], v157 offset:35840
	ds_read_b128 v[194:197], v157 offset:36864
	ds_read_b128 v[198:201], v157 offset:37888
	ds_read_b128 v[202:205], v157 offset:38912
	ds_read_b128 v[206:209], v157 offset:39936
	global_load_lds_dwordx4 v[216:217], off
	v_lshl_add_u64 v[216:217], s[22:23], 0, v[132:133]
	s_mov_b32 m0, s28
	s_nop 0
	global_load_lds_dwordx4 v[216:217], off
	s_waitcnt vmcnt(8)
	s_waitcnt lgkmcnt(0)
	s_barrier
	s_setprio 1
	s_waitcnt lgkmcnt(0)
	v_mfma_f32_16x16x32_bf16 v[126:129], v[140:143], v[178:181], v[126:129]
	v_mfma_f32_16x16x32_bf16 v[122:125], v[148:151], v[178:181], v[122:125]
	v_mfma_f32_16x16x32_bf16 v[118:121], v[140:143], v[186:189], v[118:121]
	v_mfma_f32_16x16x32_bf16 v[114:117], v[148:151], v[186:189], v[114:117]
	v_mfma_f32_16x16x32_bf16 v[98:101], v[140:143], v[194:197], v[98:101]
	v_mfma_f32_16x16x32_bf16 v[90:93], v[148:151], v[194:197], v[90:93]
	v_mfma_f32_16x16x32_bf16 v[78:81], v[140:143], v[202:205], v[78:81]
	v_mfma_f32_16x16x32_bf16 v[74:77], v[148:151], v[202:205], v[74:77]
	v_mfma_f32_16x16x32_bf16 v[126:129], v[144:147], v[182:185], v[126:129]
	v_mfma_f32_16x16x32_bf16 v[122:125], v[158:161], v[182:185], v[122:125]
	v_mfma_f32_16x16x32_bf16 v[118:121], v[144:147], v[190:193], v[118:121]
	v_mfma_f32_16x16x32_bf16 v[114:117], v[158:161], v[190:193], v[114:117]
	v_mfma_f32_16x16x32_bf16 v[98:101], v[144:147], v[198:201], v[98:101]
	v_mfma_f32_16x16x32_bf16 v[90:93], v[158:161], v[198:201], v[90:93]
	v_mfma_f32_16x16x32_bf16 v[78:81], v[144:147], v[206:209], v[78:81]
	v_mfma_f32_16x16x32_bf16 v[74:77], v[158:161], v[206:209], v[74:77]
	s_setprio 0
	s_setprio 1
	v_mfma_f32_16x16x32_bf16 v[110:113], v[162:165], v[178:181], v[110:113]
	v_mfma_f32_16x16x32_bf16 v[106:109], v[170:173], v[178:181], v[106:109]
	v_mfma_f32_16x16x32_bf16 v[102:105], v[162:165], v[186:189], v[102:105]
	v_mfma_f32_16x16x32_bf16 v[94:97], v[170:173], v[186:189], v[94:97]
	v_mfma_f32_16x16x32_bf16 v[86:89], v[162:165], v[194:197], v[86:89]
	v_mfma_f32_16x16x32_bf16 v[82:85], v[170:173], v[194:197], v[82:85]
	v_mfma_f32_16x16x32_bf16 v[70:73], v[162:165], v[202:205], v[70:73]
	v_mfma_f32_16x16x32_bf16 v[66:69], v[170:173], v[202:205], v[66:69]
	v_mfma_f32_16x16x32_bf16 v[110:113], v[166:169], v[182:185], v[110:113]
	v_mfma_f32_16x16x32_bf16 v[106:109], v[174:177], v[182:185], v[106:109]
	v_mfma_f32_16x16x32_bf16 v[102:105], v[166:169], v[190:193], v[102:105]
	v_mfma_f32_16x16x32_bf16 v[94:97], v[174:177], v[190:193], v[94:97]
	v_mfma_f32_16x16x32_bf16 v[86:89], v[166:169], v[198:201], v[86:89]
	v_mfma_f32_16x16x32_bf16 v[82:85], v[174:177], v[198:201], v[82:85]
	v_mfma_f32_16x16x32_bf16 v[70:73], v[166:169], v[206:209], v[70:73]
	v_mfma_f32_16x16x32_bf16 v[66:69], v[174:177], v[206:209], v[66:69]
	s_setprio 0
	s_barrier
; #define PG8_STAGE(bufoff, gbase, voff) do { _Pragma("unroll") for (int _i = 0; _i < 2; ++_i) \
;         __builtin_amdgcn_global_load_lds((const unsigned*)((const char*)(gbase) + (voff)[_i]), (PG8_LAS unsigned*)(lds + (bufoff) + ldsw + _i * 8192), 16, 0, 0); } while (0)
; #define PG8_LDA(dst, b, h) do { _Pragma("unroll") for (int m = 0; m < 4; ++m) _Pragma("unroll") for (int k = 0; k < 2; ++k) dst[m][k] = *(const PG8_LAS bf16x8*)(lds + PG8_SA(b, h) + aoff + m * 2048 + k * 1024); } while (0)
; #define PG8_MMA(ai, bj, At, Bt) do { __builtin_amdgcn_s_setprio(1); _Pragma("unroll") for (int m = 0; m < 4; ++m) _Pragma("unroll") for (int n = 0; n < 2; ++n) _Pragma("unroll") for (int k = 0; k < 2; ++k) \
;         acc[ai][bj][m][n] = __builtin_amdgcn_mfma_f32_16x16x32_bf16(Bt[n][k], At[m][k], acc[ai][bj][m][n], 0, 0, 0); __builtin_amdgcn_s_setprio(0); } while (0)
; #define PG8_WAIT_V(n) asm volatile("s_waitcnt vmcnt(" #n ")" ::: "memory")
; #define PG8_WAIT_L(n) asm volatile("s_waitcnt lgkmcnt(" #n ")" ::: "memory")
; #define PG8_BAR __builtin_amdgcn_s_barrier()
; #define PG8_SCHED __builtin_amdgcn_sched_barrier(0)
; template <class Epi, class Sched, bool ALIGN_EPI = false, bool SP2 = false>
; __device__ __forceinline__ void gemm_phase(PG8_LAS unsigned char* lds, const Gemm g, const Sched& S, const Epi& E, const int wv) {
;     ...
;         for (int t = 0; t < nt; t += 2) {
;             const bool last = (t == nt - 2);
;     ...
;             PG8_LDA(At, 1, 1); PG8_STAGE(PG8_SB(1, 0), b3, voffB); PG8_STAGE(PG8_SB(1, 1), b3 + hstep, voffB); PG8_STAGE(PG8_SA(1, 0), a3, voffA);
;             PG8_WAIT_V(8); PG8_WAIT_L(0); PG8_BAR; PG8_MMA(1, 0, At, B0); PG8_MMA(1, 1, At, B1); PG8_BAR; PG8_SCHED;
	s_add_i32 s22, s45, s24
	v_lshl_add_u64 v[152:153], v[152:153], 0, s[2:3]
	s_mov_b32 m0, s22
	ds_read_b128 v[178:181], v157 offset:49152
	ds_read_b128 v[182:185], v157 offset:50176
	ds_read_b128 v[186:189], v157 offset:51200
	ds_read_b128 v[190:193], v157 offset:52224
	ds_read_b128 v[194:197], v157 offset:53248
	ds_read_b128 v[198:201], v157 offset:54272
	ds_read_b128 v[202:205], v157 offset:55296
	ds_read_b128 v[206:209], v157 offset:56320
	global_load_lds_dwordx4 v[152:153], off
	s_add_i32 m0, s22, 0x2000
	s_add_u32 s20, s20, 0x40080
	v_lshl_add_u64 v[152:153], v[210:211], 0, s[2:3]
	s_addc_u32 s21, s21, 0
	s_add_i32 s22, s46, s24
	global_load_lds_dwordx4 v[152:153], off
	v_lshl_add_u64 v[152:153], s[20:21], 0, v[0:1]
	s_mov_b32 m0, s22
	s_nop 0
	global_load_lds_dwordx4 v[152:153], off
	v_lshl_add_u64 v[152:153], s[20:21], 0, v[130:131]
	s_add_i32 m0, s22, 0x2000
	s_nop 0
	global_load_lds_dwordx4 v[152:153], off
	v_lshl_add_u64 v[152:153], v[212:213], 0, s[2:3]
	s_mov_b32 m0, s33
	s_nop 0
	global_load_lds_dwordx4 v[152:153], off
	v_lshl_add_u64 v[152:153], v[214:215], 0, s[2:3]
	s_mov_b32 m0, s35
	s_nop 0
	global_load_lds_dwordx4 v[152:153], off
	s_waitcnt vmcnt(8)
	s_waitcnt lgkmcnt(0)
	s_barrier
	s_setprio 1
	s_waitcnt lgkmcnt(0)
	v_mfma_f32_16x16x32_bf16 v[62:65], v[140:143], v[178:181], v[62:65]
	v_mfma_f32_16x16x32_bf16 v[58:61], v[148:151], v[178:181], v[58:61]
	v_mfma_f32_16x16x32_bf16 v[46:49], v[140:143], v[186:189], v[46:49]
	v_mfma_f32_16x16x32_bf16 v[42:45], v[148:151], v[186:189], v[42:45]
	v_mfma_f32_16x16x32_bf16 v[30:33], v[140:143], v[194:197], v[30:33]
	v_mfma_f32_16x16x32_bf16 v[26:29], v[148:151], v[194:197], v[26:29]
	v_mfma_f32_16x16x32_bf16 v[14:17], v[140:143], v[202:205], v[14:17]
	v_mfma_f32_16x16x32_bf16 v[10:13], v[148:151], v[202:205], v[10:13]
	v_mfma_f32_16x16x32_bf16 v[62:65], v[144:147], v[182:185], v[62:65]
	v_mfma_f32_16x16x32_bf16 v[58:61], v[158:161], v[182:185], v[58:61]
	v_mfma_f32_16x16x32_bf16 v[46:49], v[144:147], v[190:193], v[46:49]
	v_mfma_f32_16x16x32_bf16 v[42:45], v[158:161], v[190:193], v[42:45]
	v_mfma_f32_16x16x32_bf16 v[30:33], v[144:147], v[198:201], v[30:33]
	v_mfma_f32_16x16x32_bf16 v[26:29], v[158:161], v[198:201], v[26:29]
	v_mfma_f32_16x16x32_bf16 v[14:17], v[144:147], v[206:209], v[14:17]
	v_mfma_f32_16x16x32_bf16 v[10:13], v[158:161], v[206:209], v[10:13]
	s_setprio 0
	s_setprio 1
	v_mfma_f32_16x16x32_bf16 v[54:57], v[162:165], v[178:181], v[54:57]
	v_mfma_f32_16x16x32_bf16 v[50:53], v[170:173], v[178:181], v[50:53]
	v_mfma_f32_16x16x32_bf16 v[38:41], v[162:165], v[186:189], v[38:41]
	v_mfma_f32_16x16x32_bf16 v[34:37], v[170:173], v[186:189], v[34:37]
	v_mfma_f32_16x16x32_bf16 v[22:25], v[162:165], v[194:197], v[22:25]
	v_mfma_f32_16x16x32_bf16 v[18:21], v[170:173], v[194:197], v[18:21]
	v_mfma_f32_16x16x32_bf16 v[6:9], v[162:165], v[202:205], v[6:9]
	v_mfma_f32_16x16x32_bf16 v[2:5], v[170:173], v[202:205], v[2:5]
	v_mfma_f32_16x16x32_bf16 v[54:57], v[166:169], v[182:185], v[54:57]
	v_mfma_f32_16x16x32_bf16 v[50:53], v[174:177], v[182:185], v[50:53]
	v_mfma_f32_16x16x32_bf16 v[38:41], v[166:169], v[190:193], v[38:41]
	v_mfma_f32_16x16x32_bf16 v[34:37], v[174:177], v[190:193], v[34:37]
	v_mfma_f32_16x16x32_bf16 v[22:25], v[166:169], v[198:201], v[22:25]
	v_mfma_f32_16x16x32_bf16 v[18:21], v[174:177], v[198:201], v[18:21]
	v_mfma_f32_16x16x32_bf16 v[6:9], v[166:169], v[206:209], v[6:9]
	v_mfma_f32_16x16x32_bf16 v[2:5], v[174:177], v[206:209], v[2:5]
	s_setprio 0
	s_add_i32 s44, s44, 2
	s_add_u32 s18, s18, 0x100
	s_addc_u32 s19, s19, 0
	s_add_u32 s42, s42, 0x100
	s_addc_u32 s43, s43, 0
	s_cmp_gt_u32 s44, 13
	s_barrier
	s_cbranch_scc0 .LBB0_156
	s_and_b64 vcc, exec, s[6:7]
	s_cbranch_vccz .LBB0_159
	s_barrier

; #define PG8_STAGE(bufoff, gbase, voff) do { _Pragma("unroll") for (int _i = 0; _i < 2; ++_i) \
;         __builtin_amdgcn_global_load_lds((const unsigned*)((const char*)(gbase) + (voff)[_i]), (PG8_LAS unsigned*)(lds + (bufoff) + ldsw + _i * 8192), 16, 0, 0); } while (0)
; #define PG8_LDA(dst, b, h) do { _Pragma("unroll") for (int m = 0; m < 4; ++m) _Pragma("unroll") for (int k = 0; k < 2; ++k) dst[m][k] = *(const PG8_LAS bf16x8*)(lds + PG8_SA(b, h) + aoff + m * 2048 + k * 1024); } while (0)
; #define PG8_LDB(dst, b, h) do { _Pragma("unroll") for (int n = 0; n < 2; ++n) _Pragma("unroll") for (int k = 0; k < 2; ++k) dst[n][k] = *(const PG8_LAS bf16x8*)(lds + PG8_SB(b, h) + boff + n * 2048 + k * 1024); } while (0)
; #define PG8_MMA(ai, bj, At, Bt) do { __builtin_amdgcn_s_setprio(1); _Pragma("unroll") for (int m = 0; m < 4; ++m) _Pragma("unroll") for (int n = 0; n < 2; ++n) _Pragma("unroll") for (int k = 0; k < 2; ++k) \
;         acc[ai][bj][m][n] = __builtin_amdgcn_mfma_f32_16x16x32_bf16(Bt[n][k], At[m][k], acc[ai][bj][m][n], 0, 0, 0); __builtin_amdgcn_s_setprio(0); } while (0)
; #define PG8_WAIT_V(n) asm volatile("s_waitcnt vmcnt(" #n ")" ::: "memory")
; #define PG8_WAIT_L(n) asm volatile("s_waitcnt lgkmcnt(" #n ")" ::: "memory")
; template <class Epi, class Sched, bool ALIGN_EPI = false, bool SP2 = false>
; __device__ __forceinline__ void gemm_phase(PG8_LAS unsigned char* lds, const Gemm g, const Sched& S, const Epi& E, const int wv) {
;     ...
;             const bool last = (t == nt - 2);
;             const char* a1 = cA + (size_t)(t + 1) * kstep;
;             const char* a2 = last ? nA : cA + (size_t)(t + 2) * kstep; const char* b2 = last ? nB : cB + (size_t)(t + 2) * kstep;
;             const char* a3 = a2 + kstep; const char* b3 = b2 + kstep;
;             if (last && has_next) S.a_ready(nxt);
;             if constexpr (SP2) {
;             PG8_LDB(B0, 0, 0); PG8_LDB(B1, 0, 1); PG8_SCHED; PG8_LDA(At, 0, 0); PG8_STAGE(PG8_SA(1, 1), a1 + hstep, voffA);
;             PG8_WAIT_V(8); PG8_WAIT_L(0); PG8_BAR; PG8_MMA(0, 0, At, B0); PG8_MMA(0, 1, At, B1); PG8_BAR; PG8_SCHED;
;             PG8_LDA(At, 0, 1); PG8_STAGE(PG8_SB(0, 0), b2, voffB); PG8_STAGE(PG8_SB(0, 1), b2 + hstep, voffB); PG8_STAGE(PG8_SA(0, 0), a2, voffA);
;             PG8_WAIT_V(8); PG8_WAIT_L(0); PG8_BAR; PG8_MMA(1, 0, At, B0); PG8_MMA(1, 1, At, B1); PG8_BAR; PG8_SCHED;
.LBB0_350:
	s_add_u32 s24, s22, 0xfffc0080
	s_addc_u32 s25, s23, -1
	s_add_i32 s48, 0, 0x10000
	s_cmp_eq_u32 s47, 12
	s_cselect_b32 s27, s13, s25
	s_cselect_b32 s26, s19, s24
	s_cselect_b32 s25, s11, s46
	s_cselect_b32 s24, s33, s45
	s_add_i32 s50, 0, 0x14000
	v_add_u32_e32 v126, s48, v183
	v_add_u32_e32 v168, s50, v183
	ds_read_b128 v[114:117], v126
	ds_read_b128 v[118:121], v126 offset:1024
	ds_read_b128 v[122:125], v126 offset:2048
	ds_read_b128 v[126:129], v126 offset:3072
	ds_read_b128 v[130:133], v168
	ds_read_b128 v[134:137], v168 offset:1024
	ds_read_b128 v[164:167], v168 offset:2048
	ds_read_b128 v[168:171], v168 offset:3072
	v_lshl_add_u64 v[180:181], s[22:23], 0, v[160:161]
	s_add_i32 m0, s21, 0xc000
	ds_read_b128 v[172:175], v185
	ds_read_b128 v[176:179], v185 offset:1024
	ds_read_b128 v[186:189], v185 offset:2048
	ds_read_b128 v[190:193], v185 offset:3072
	ds_read_b128 v[194:197], v185 offset:4096
	ds_read_b128 v[198:201], v185 offset:5120
	ds_read_b128 v[202:205], v185 offset:6144
	ds_read_b128 v[206:209], v185 offset:7168
	global_load_lds_dwordx4 v[180:181], off
	v_lshl_add_u64 v[180:181], s[22:23], 0, v[162:163]
	s_add_i32 m0, s21, 0xe000
	s_nop 0
	global_load_lds_dwordx4 v[180:181], off
	s_waitcnt vmcnt(8)
	s_waitcnt lgkmcnt(0)
	s_barrier
	s_setprio 1
	s_waitcnt lgkmcnt(0)
	v_mfma_f32_16x16x32_bf16 v[150:153], v[114:117], v[172:175], v[150:153]
	v_mfma_f32_16x16x32_bf16 v[146:149], v[122:125], v[172:175], v[146:149]
	v_mfma_f32_16x16x32_bf16 v[110:113], v[114:117], v[186:189], v[110:113]
	v_mfma_f32_16x16x32_bf16 v[106:109], v[122:125], v[186:189], v[106:109]
	v_mfma_f32_16x16x32_bf16 v[94:97], v[114:117], v[194:197], v[94:97]
	v_mfma_f32_16x16x32_bf16 v[90:93], v[122:125], v[194:197], v[90:93]
	v_mfma_f32_16x16x32_bf16 v[78:81], v[114:117], v[202:205], v[78:81]
	v_mfma_f32_16x16x32_bf16 v[74:77], v[122:125], v[202:205], v[74:77]
	v_mfma_f32_16x16x32_bf16 v[150:153], v[118:121], v[176:179], v[150:153]
	v_mfma_f32_16x16x32_bf16 v[146:149], v[126:129], v[176:179], v[146:149]
	v_mfma_f32_16x16x32_bf16 v[110:113], v[118:121], v[190:193], v[110:113]
	v_mfma_f32_16x16x32_bf16 v[106:109], v[126:129], v[190:193], v[106:109]
	v_mfma_f32_16x16x32_bf16 v[94:97], v[118:121], v[198:201], v[94:97]
	v_mfma_f32_16x16x32_bf16 v[90:93], v[126:129], v[198:201], v[90:93]
	v_mfma_f32_16x16x32_bf16 v[78:81], v[118:121], v[206:209], v[78:81]
	v_mfma_f32_16x16x32_bf16 v[74:77], v[126:129], v[206:209], v[74:77]
	s_setprio 0
	s_setprio 1
	v_mfma_f32_16x16x32_bf16 v[142:145], v[130:133], v[172:175], v[142:145]
	v_mfma_f32_16x16x32_bf16 v[138:141], v[164:167], v[172:175], v[138:141]
	v_mfma_f32_16x16x32_bf16 v[102:105], v[130:133], v[186:189], v[102:105]
	v_mfma_f32_16x16x32_bf16 v[98:101], v[164:167], v[186:189], v[98:101]
	v_mfma_f32_16x16x32_bf16 v[86:89], v[130:133], v[194:197], v[86:89]
	v_mfma_f32_16x16x32_bf16 v[82:85], v[164:167], v[194:197], v[82:85]
	v_mfma_f32_16x16x32_bf16 v[70:73], v[130:133], v[202:205], v[70:73]
	v_mfma_f32_16x16x32_bf16 v[66:69], v[164:167], v[202:205], v[66:69]
	v_mfma_f32_16x16x32_bf16 v[142:145], v[134:137], v[176:179], v[142:145]
	v_mfma_f32_16x16x32_bf16 v[138:141], v[168:171], v[176:179], v[138:141]
	v_mfma_f32_16x16x32_bf16 v[102:105], v[134:137], v[190:193], v[102:105]
	v_mfma_f32_16x16x32_bf16 v[98:101], v[168:171], v[190:193], v[98:101]
	v_mfma_f32_16x16x32_bf16 v[86:89], v[134:137], v[198:201], v[86:89]
	v_mfma_f32_16x16x32_bf16 v[82:85], v[168:171], v[198:201], v[82:85]
	v_mfma_f32_16x16x32_bf16 v[70:73], v[134:137], v[206:209], v[70:73]
	v_mfma_f32_16x16x32_bf16 v[66:69], v[168:171], v[206:209], v[66:69]
	s_setprio 0
	s_barrier
	s_add_i32 s48, s48, s36
	v_lshl_add_u64 v[180:181], s[24:25], 0, v[0:1]
	s_mov_b32 m0, s48
	ds_read_b128 v[172:175], v185 offset:16384
	ds_read_b128 v[176:179], v185 offset:17408
	ds_read_b128 v[186:189], v185 offset:18432
	ds_read_b128 v[190:193], v185 offset:19456
	ds_read_b128 v[194:197], v185 offset:20480
	ds_read_b128 v[198:201], v185 offset:21504
	ds_read_b128 v[202:205], v185 offset:22528
	ds_read_b128 v[206:209], v185 offset:23552
	global_load_lds_dwordx4 v[180:181], off
	s_add_i32 m0, s48, 0x2000
	s_add_u32 s48, s24, 0x40000
	v_lshl_add_u64 v[210:211], s[24:25], 0, v[158:159]
	s_addc_u32 s49, s25, 0
	s_add_i32 s50, s50, s36
	global_load_lds_dwordx4 v[210:211], off
	v_lshl_add_u64 v[212:213], s[48:49], 0, v[0:1]
	s_mov_b32 m0, s50
	v_lshl_add_u64 v[214:215], s[26:27], 0, v[156:157]
	global_load_lds_dwordx4 v[212:213], off
	v_lshl_add_u64 v[212:213], s[48:49], 0, v[158:159]
	s_add_i32 m0, s50, 0x2000
	s_nop 0
	global_load_lds_dwordx4 v[212:213], off
	v_lshl_add_u64 v[212:213], s[26:27], 0, v[154:155]
	s_mov_b32 m0, s21
	s_nop 0
	global_load_lds_dwordx4 v[212:213], off
	s_mov_b32 m0, s37
	s_nop 0
	global_load_lds_dwordx4 v[214:215], off
	s_waitcnt vmcnt(8)
	s_waitcnt lgkmcnt(0)
	s_barrier
; #define PG8_STAGE(bufoff, gbase, voff) do { _Pragma("unroll") for (int _i = 0; _i < 2; ++_i) \
;         __builtin_amdgcn_global_load_lds((const unsigned*)((const char*)(gbase) + (voff)[_i]), (PG8_LAS unsigned*)(lds + (bufoff) + ldsw + _i * 8192), 16, 0, 0); } while (0)
; #define PG8_LDA(dst, b, h) do { _Pragma("unroll") for (int m = 0; m < 4; ++m) _Pragma("unroll") for (int k = 0; k < 2; ++k) dst[m][k] = *(const PG8_LAS bf16x8*)(lds + PG8_SA(b, h) + aoff + m * 2048 + k * 1024); } while (0)
; #define PG8_LDB(dst, b, h) do { _Pragma("unroll") for (int n = 0; n < 2; ++n) _Pragma("unroll") for (int k = 0; k < 2; ++k) dst[n][k] = *(const PG8_LAS bf16x8*)(lds + PG8_SB(b, h) + boff + n * 2048 + k * 1024); } while (0)
; #define PG8_MMA(ai, bj, At, Bt) do { __builtin_amdgcn_s_setprio(1); _Pragma("unroll") for (int m = 0; m < 4; ++m) _Pragma("unroll") for (int n = 0; n < 2; ++n) _Pragma("unroll") for (int k = 0; k < 2; ++k) \
;         acc[ai][bj][m][n] = __builtin_amdgcn_mfma_f32_16x16x32_bf16(Bt[n][k], At[m][k], acc[ai][bj][m][n], 0, 0, 0); __builtin_amdgcn_s_setprio(0); } while (0)
; #define PG8_WAIT_V(n) asm volatile("s_waitcnt vmcnt(" #n ")" ::: "memory")
; #define PG8_WAIT_L(n) asm volatile("s_waitcnt lgkmcnt(" #n ")" ::: "memory")
; #define PG8_BAR __builtin_amdgcn_s_barrier()
; #define PG8_SCHED __builtin_amdgcn_sched_barrier(0)
; template <class Epi, class Sched, bool ALIGN_EPI = false, bool SP2 = false>
; __device__ __forceinline__ void gemm_phase(PG8_LAS unsigned char* lds, const Gemm g, const Sched& S, const Epi& E, const int wv) {
;     ...
;             PG8_WAIT_V(8); PG8_WAIT_L(0); PG8_BAR; PG8_MMA(1, 0, At, B0); PG8_MMA(1, 1, At, B1); PG8_BAR; PG8_SCHED;
;             PG8_LDB(B0, 1, 0); PG8_LDB(B1, 1, 1); PG8_SCHED; PG8_LDA(At, 1, 0); PG8_STAGE(PG8_SA(0, 1), a2 + hstep, voffA);
;             PG8_WAIT_V(8); PG8_WAIT_L(0); PG8_BAR; PG8_MMA(0, 0, At, B0); PG8_MMA(0, 1, At, B1); PG8_BAR; PG8_SCHED;
	s_setprio 1
	s_waitcnt lgkmcnt(0)
	v_mfma_f32_16x16x32_bf16 v[62:65], v[114:117], v[172:175], v[62:65]
	v_mfma_f32_16x16x32_bf16 v[58:61], v[122:125], v[172:175], v[58:61]
	v_mfma_f32_16x16x32_bf16 v[46:49], v[114:117], v[186:189], v[46:49]
	v_mfma_f32_16x16x32_bf16 v[42:45], v[122:125], v[186:189], v[42:45]
	v_mfma_f32_16x16x32_bf16 v[30:33], v[114:117], v[194:197], v[30:33]
	v_mfma_f32_16x16x32_bf16 v[26:29], v[122:125], v[194:197], v[26:29]
	v_mfma_f32_16x16x32_bf16 v[14:17], v[114:117], v[202:205], v[14:17]
	v_mfma_f32_16x16x32_bf16 v[10:13], v[122:125], v[202:205], v[10:13]
	v_mfma_f32_16x16x32_bf16 v[62:65], v[118:121], v[176:179], v[62:65]
	v_mfma_f32_16x16x32_bf16 v[58:61], v[126:129], v[176:179], v[58:61]
	v_mfma_f32_16x16x32_bf16 v[46:49], v[118:121], v[190:193], v[46:49]
	v_mfma_f32_16x16x32_bf16 v[42:45], v[126:129], v[190:193], v[42:45]
	v_mfma_f32_16x16x32_bf16 v[30:33], v[118:121], v[198:201], v[30:33]
	v_mfma_f32_16x16x32_bf16 v[26:29], v[126:129], v[198:201], v[26:29]
	v_mfma_f32_16x16x32_bf16 v[14:17], v[118:121], v[206:209], v[14:17]
	v_mfma_f32_16x16x32_bf16 v[10:13], v[126:129], v[206:209], v[10:13]
	s_setprio 0
	s_setprio 1
	v_mfma_f32_16x16x32_bf16 v[54:57], v[130:133], v[172:175], v[54:57]
	v_mfma_f32_16x16x32_bf16 v[50:53], v[164:167], v[172:175], v[50:53]
	v_mfma_f32_16x16x32_bf16 v[38:41], v[130:133], v[186:189], v[38:41]
	v_mfma_f32_16x16x32_bf16 v[34:37], v[164:167], v[186:189], v[34:37]
	v_mfma_f32_16x16x32_bf16 v[22:25], v[130:133], v[194:197], v[22:25]
	v_mfma_f32_16x16x32_bf16 v[18:21], v[164:167], v[194:197], v[18:21]
	v_mfma_f32_16x16x32_bf16 v[6:9], v[130:133], v[202:205], v[6:9]
	v_mfma_f32_16x16x32_bf16 v[2:5], v[164:167], v[202:205], v[2:5]
	v_mfma_f32_16x16x32_bf16 v[54:57], v[134:137], v[176:179], v[54:57]
	v_mfma_f32_16x16x32_bf16 v[50:53], v[168:171], v[176:179], v[50:53]
	v_mfma_f32_16x16x32_bf16 v[38:41], v[134:137], v[190:193], v[38:41]
	v_mfma_f32_16x16x32_bf16 v[34:37], v[168:171], v[190:193], v[34:37]
	v_mfma_f32_16x16x32_bf16 v[22:25], v[134:137], v[198:201], v[22:25]
	v_mfma_f32_16x16x32_bf16 v[18:21], v[168:171], v[198:201], v[18:21]
	v_mfma_f32_16x16x32_bf16 v[6:9], v[134:137], v[206:209], v[6:9]
	v_mfma_f32_16x16x32_bf16 v[2:5], v[168:171], v[206:209], v[2:5]
	s_setprio 0
	s_barrier
	s_add_i32 s48, 0, 0x18000
	s_add_i32 s49, 0, 0x1c000
	v_add_u32_e32 v126, s48, v183
	v_add_u32_e32 v168, s49, v183
	ds_read_b128 v[114:117], v126
	ds_read_b128 v[118:121], v126 offset:1024
	ds_read_b128 v[122:125], v126 offset:2048
	ds_read_b128 v[126:129], v126 offset:3072
	ds_read_b128 v[130:133], v168
	ds_read_b128 v[134:137], v168 offset:1024
	ds_read_b128 v[164:167], v168 offset:2048
	ds_read_b128 v[168:171], v168 offset:3072
	s_add_u32 s26, s26, 0x40000
	s_addc_u32 s27, s27, 0
	s_mov_b32 m0, s38
	v_lshl_add_u64 v[216:217], s[26:27], 0, v[154:155]
	ds_read_b128 v[172:175], v185 offset:32768
	ds_read_b128 v[176:179], v185 offset:33792
	ds_read_b128 v[186:189], v185 offset:34816
	ds_read_b128 v[190:193], v185 offset:35840
	ds_read_b128 v[194:197], v185 offset:36864
	ds_read_b128 v[198:201], v185 offset:37888
	ds_read_b128 v[202:205], v185 offset:38912
	ds_read_b128 v[206:209], v185 offset:39936
	global_load_lds_dwordx4 v[216:217], off
	v_lshl_add_u64 v[216:217], s[26:27], 0, v[156:157]
	s_mov_b32 m0, s39
	s_nop 0
	global_load_lds_dwordx4 v[216:217], off
	s_waitcnt vmcnt(8)
	s_waitcnt lgkmcnt(0)
	s_barrier
	s_setprio 1
	s_waitcnt lgkmcnt(0)
	v_mfma_f32_16x16x32_bf16 v[150:153], v[114:117], v[172:175], v[150:153]
	v_mfma_f32_16x16x32_bf16 v[146:149], v[122:125], v[172:175], v[146:149]
	v_mfma_f32_16x16x32_bf16 v[110:113], v[114:117], v[186:189], v[110:113]
	v_mfma_f32_16x16x32_bf16 v[106:109], v[122:125], v[186:189], v[106:109]
	v_mfma_f32_16x16x32_bf16 v[94:97], v[114:117], v[194:197], v[94:97]
	v_mfma_f32_16x16x32_bf16 v[90:93], v[122:125], v[194:197], v[90:93]
	v_mfma_f32_16x16x32_bf16 v[78:81], v[114:117], v[202:205], v[78:81]
	v_mfma_f32_16x16x32_bf16 v[74:77], v[122:125], v[202:205], v[74:77]
	v_mfma_f32_16x16x32_bf16 v[150:153], v[118:121], v[176:179], v[150:153]
	v_mfma_f32_16x16x32_bf16 v[146:149], v[126:129], v[176:179], v[146:149]
	v_mfma_f32_16x16x32_bf16 v[110:113], v[118:121], v[190:193], v[110:113]
	v_mfma_f32_16x16x32_bf16 v[106:109], v[126:129], v[190:193], v[106:109]
	v_mfma_f32_16x16x32_bf16 v[94:97], v[118:121], v[198:201], v[94:97]
	v_mfma_f32_16x16x32_bf16 v[90:93], v[126:129], v[198:201], v[90:93]
	v_mfma_f32_16x16x32_bf16 v[78:81], v[118:121], v[206:209], v[78:81]
	v_mfma_f32_16x16x32_bf16 v[74:77], v[126:129], v[206:209], v[74:77]
	s_setprio 0
	s_setprio 1
	v_mfma_f32_16x16x32_bf16 v[142:145], v[130:133], v[172:175], v[142:145]
	v_mfma_f32_16x16x32_bf16 v[138:141], v[164:167], v[172:175], v[138:141]
	v_mfma_f32_16x16x32_bf16 v[102:105], v[130:133], v[186:189], v[102:105]
	v_mfma_f32_16x16x32_bf16 v[98:101], v[164:167], v[186:189], v[98:101]
	v_mfma_f32_16x16x32_bf16 v[86:89], v[130:133], v[194:197], v[86:89]
	v_mfma_f32_16x16x32_bf16 v[82:85], v[164:167], v[194:197], v[82:85]
	v_mfma_f32_16x16x32_bf16 v[70:73], v[130:133], v[202:205], v[70:73]
	v_mfma_f32_16x16x32_bf16 v[66:69], v[164:167], v[202:205], v[66:69]
	v_mfma_f32_16x16x32_bf16 v[142:145], v[134:137], v[176:179], v[142:145]
	v_mfma_f32_16x16x32_bf16 v[138:141], v[168:171], v[176:179], v[138:141]
	v_mfma_f32_16x16x32_bf16 v[102:105], v[134:137], v[190:193], v[102:105]
	v_mfma_f32_16x16x32_bf16 v[98:101], v[168:171], v[190:193], v[98:101]
	v_mfma_f32_16x16x32_bf16 v[86:89], v[134:137], v[198:201], v[86:89]
	v_mfma_f32_16x16x32_bf16 v[82:85], v[168:171], v[198:201], v[82:85]
	v_mfma_f32_16x16x32_bf16 v[70:73], v[134:137], v[206:209], v[70:73]
	v_mfma_f32_16x16x32_bf16 v[66:69], v[168:171], v[206:209], v[66:69]
	s_setprio 0
	s_barrier
; #define PG8_STAGE(bufoff, gbase, voff) do { _Pragma("unroll") for (int _i = 0; _i < 2; ++_i) \
;         __builtin_amdgcn_global_load_lds((const unsigned*)((const char*)(gbase) + (voff)[_i]), (PG8_LAS unsigned*)(lds + (bufoff) + ldsw + _i * 8192), 16, 0, 0); } while (0)
; #define PG8_LDA(dst, b, h) do { _Pragma("unroll") for (int m = 0; m < 4; ++m) _Pragma("unroll") for (int k = 0; k < 2; ++k) dst[m][k] = *(const PG8_LAS bf16x8*)(lds + PG8_SA(b, h) + aoff + m * 2048 + k * 1024); } while (0)
; #define PG8_MMA(ai, bj, At, Bt) do { __builtin_amdgcn_s_setprio(1); _Pragma("unroll") for (int m = 0; m < 4; ++m) _Pragma("unroll") for (int n = 0; n < 2; ++n) _Pragma("unroll") for (int k = 0; k < 2; ++k) \
;         acc[ai][bj][m][n] = __builtin_amdgcn_mfma_f32_16x16x32_bf16(Bt[n][k], At[m][k], acc[ai][bj][m][n], 0, 0, 0); __builtin_amdgcn_s_setprio(0); } while (0)
; #define PG8_WAIT_V(n) asm volatile("s_waitcnt vmcnt(" #n ")" ::: "memory")
; #define PG8_WAIT_L(n) asm volatile("s_waitcnt lgkmcnt(" #n ")" ::: "memory")
; #define PG8_BAR __builtin_amdgcn_s_barrier()
; #define PG8_SCHED __builtin_amdgcn_sched_barrier(0)
; template <class Epi, class Sched, bool ALIGN_EPI = false, bool SP2 = false>
; __device__ __forceinline__ void gemm_phase(PG8_LAS unsigned char* lds, const Gemm g, const Sched& S, const Epi& E, const int wv) {
;     ...
;             PG8_LDA(At, 1, 1); PG8_STAGE(PG8_SB(1, 0), b3, voffB); PG8_STAGE(PG8_SB(1, 1), b3 + hstep, voffB); PG8_STAGE(PG8_SA(1, 0), a3, voffA);
;             PG8_WAIT_V(8); PG8_WAIT_L(0); PG8_BAR; PG8_MMA(1, 0, At, B0); PG8_MMA(1, 1, At, B1); PG8_BAR; PG8_SCHED;
;     ...
;         if constexpr (ALIGN_EPI) { if (wr == 0) PG8_BAR; }
	s_add_i32 s26, s48, s36
	v_lshl_add_u64 v[180:181], v[180:181], 0, s[2:3]
	s_mov_b32 m0, s26
	ds_read_b128 v[172:175], v185 offset:49152
	ds_read_b128 v[176:179], v185 offset:50176
	ds_read_b128 v[186:189], v185 offset:51200
	ds_read_b128 v[190:193], v185 offset:52224
	ds_read_b128 v[194:197], v185 offset:53248
	ds_read_b128 v[198:201], v185 offset:54272
	ds_read_b128 v[202:205], v185 offset:55296
	ds_read_b128 v[206:209], v185 offset:56320
	global_load_lds_dwordx4 v[180:181], off
	s_add_i32 m0, s26, 0x2000
	s_add_u32 s24, s24, 0x40080
	v_lshl_add_u64 v[180:181], v[210:211], 0, s[2:3]
	s_addc_u32 s25, s25, 0
	s_add_i32 s26, s49, s36
	global_load_lds_dwordx4 v[180:181], off
	v_lshl_add_u64 v[180:181], s[24:25], 0, v[0:1]
	s_mov_b32 m0, s26
	s_nop 0
	global_load_lds_dwordx4 v[180:181], off
	v_lshl_add_u64 v[180:181], s[24:25], 0, v[158:159]
	s_add_i32 m0, s26, 0x2000
	s_nop 0
	global_load_lds_dwordx4 v[180:181], off
	v_lshl_add_u64 v[180:181], v[212:213], 0, s[2:3]
	s_mov_b32 m0, s40
	s_nop 0
	global_load_lds_dwordx4 v[180:181], off
	v_lshl_add_u64 v[180:181], v[214:215], 0, s[2:3]
	s_mov_b32 m0, s41
	s_nop 0
	global_load_lds_dwordx4 v[180:181], off
	s_waitcnt vmcnt(8)
	s_waitcnt lgkmcnt(0)
	s_barrier
	s_setprio 1
	s_waitcnt lgkmcnt(0)
	v_mfma_f32_16x16x32_bf16 v[62:65], v[114:117], v[172:175], v[62:65]
	v_mfma_f32_16x16x32_bf16 v[58:61], v[122:125], v[172:175], v[58:61]
	v_mfma_f32_16x16x32_bf16 v[46:49], v[114:117], v[186:189], v[46:49]
	v_mfma_f32_16x16x32_bf16 v[42:45], v[122:125], v[186:189], v[42:45]
	v_mfma_f32_16x16x32_bf16 v[30:33], v[114:117], v[194:197], v[30:33]
	v_mfma_f32_16x16x32_bf16 v[26:29], v[122:125], v[194:197], v[26:29]
	v_mfma_f32_16x16x32_bf16 v[14:17], v[114:117], v[202:205], v[14:17]
	v_mfma_f32_16x16x32_bf16 v[10:13], v[122:125], v[202:205], v[10:13]
	v_mfma_f32_16x16x32_bf16 v[62:65], v[118:121], v[176:179], v[62:65]
	v_mfma_f32_16x16x32_bf16 v[58:61], v[126:129], v[176:179], v[58:61]
	v_mfma_f32_16x16x32_bf16 v[46:49], v[118:121], v[190:193], v[46:49]
	v_mfma_f32_16x16x32_bf16 v[42:45], v[126:129], v[190:193], v[42:45]
	v_mfma_f32_16x16x32_bf16 v[30:33], v[118:121], v[198:201], v[30:33]
	v_mfma_f32_16x16x32_bf16 v[26:29], v[126:129], v[198:201], v[26:29]
	v_mfma_f32_16x16x32_bf16 v[14:17], v[118:121], v[206:209], v[14:17]
	v_mfma_f32_16x16x32_bf16 v[10:13], v[126:129], v[206:209], v[10:13]
	s_setprio 0
	s_setprio 1
	v_mfma_f32_16x16x32_bf16 v[54:57], v[130:133], v[172:175], v[54:57]
	v_mfma_f32_16x16x32_bf16 v[50:53], v[164:167], v[172:175], v[50:53]
	v_mfma_f32_16x16x32_bf16 v[38:41], v[130:133], v[186:189], v[38:41]
	v_mfma_f32_16x16x32_bf16 v[34:37], v[164:167], v[186:189], v[34:37]
	v_mfma_f32_16x16x32_bf16 v[22:25], v[130:133], v[194:197], v[22:25]
	v_mfma_f32_16x16x32_bf16 v[18:21], v[164:167], v[194:197], v[18:21]
	v_mfma_f32_16x16x32_bf16 v[6:9], v[130:133], v[202:205], v[6:9]
	v_mfma_f32_16x16x32_bf16 v[2:5], v[164:167], v[202:205], v[2:5]
	v_mfma_f32_16x16x32_bf16 v[54:57], v[134:137], v[176:179], v[54:57]
	v_mfma_f32_16x16x32_bf16 v[50:53], v[168:171], v[176:179], v[50:53]
	v_mfma_f32_16x16x32_bf16 v[38:41], v[134:137], v[190:193], v[38:41]
	v_mfma_f32_16x16x32_bf16 v[34:37], v[168:171], v[190:193], v[34:37]
	v_mfma_f32_16x16x32_bf16 v[22:25], v[134:137], v[198:201], v[22:25]
	v_mfma_f32_16x16x32_bf16 v[18:21], v[168:171], v[198:201], v[18:21]
	v_mfma_f32_16x16x32_bf16 v[6:9], v[134:137], v[206:209], v[6:9]
	v_mfma_f32_16x16x32_bf16 v[2:5], v[168:171], v[206:209], v[2:5]
	s_setprio 0
	s_add_i32 s47, s47, 2
	s_add_u32 s22, s22, 0x100
	s_addc_u32 s23, s23, 0
	s_add_u32 s45, s45, 0x100
	s_addc_u32 s46, s46, 0
	s_cmp_gt_u32 s47, 13
	s_barrier
	s_cbranch_scc0 .LBB0_350
	s_and_b64 vcc, exec, s[8:9]
	s_cbranch_vccz .LBB0_353
	s_barrier

; #define PG8_STAGE(bufoff, gbase, voff) do { _Pragma("unroll") for (int _i = 0; _i < 2; ++_i) \
;         __builtin_amdgcn_global_load_lds((const unsigned*)((const char*)(gbase) + (voff)[_i]), (PG8_LAS unsigned*)(lds + (bufoff) + ldsw + _i * 8192), 16, 0, 0); } while (0)
; #define PG8_LDA(dst, b, h) do { _Pragma("unroll") for (int m = 0; m < 4; ++m) _Pragma("unroll") for (int k = 0; k < 2; ++k) dst[m][k] = *(const PG8_LAS bf16x8*)(lds + PG8_SA(b, h) + aoff + m * 2048 + k * 1024); } while (0)
; #define PG8_LDB(dst, b, h) do { _Pragma("unroll") for (int n = 0; n < 2; ++n) _Pragma("unroll") for (int k = 0; k < 2; ++k) dst[n][k] = *(const PG8_LAS bf16x8*)(lds + PG8_SB(b, h) + boff + n * 2048 + k * 1024); } while (0)
; #define PG8_MMA(ai, bj, At, Bt) do { __builtin_amdgcn_s_setprio(1); _Pragma("unroll") for (int m = 0; m < 4; ++m) _Pragma("unroll") for (int n = 0; n < 2; ++n) _Pragma("unroll") for (int k = 0; k < 2; ++k) \
;         acc[ai][bj][m][n] = __builtin_amdgcn_mfma_f32_16x16x32_bf16(Bt[n][k], At[m][k], acc[ai][bj][m][n], 0, 0, 0); __builtin_amdgcn_s_setprio(0); } while (0)
; #define PG8_WAIT_V(n) asm volatile("s_waitcnt vmcnt(" #n ")" ::: "memory")
; #define PG8_WAIT_L(n) asm volatile("s_waitcnt lgkmcnt(" #n ")" ::: "memory")
; template <class Epi, class Sched, bool ALIGN_EPI = false, bool SP2 = false>
; __device__ __forceinline__ void gemm_phase(PG8_LAS unsigned char* lds, const Gemm g, const Sched& S, const Epi& E, const int wv) {
;     ...
;             const bool last = (t == nt - 2);
;             const char* a1 = cA + (size_t)(t + 1) * kstep;
;             const char* a2 = last ? nA : cA + (size_t)(t + 2) * kstep; const char* b2 = last ? nB : cB + (size_t)(t + 2) * kstep;
;             const char* a3 = a2 + kstep; const char* b3 = b2 + kstep;
;             if (last && has_next) S.a_ready(nxt);
;             if constexpr (SP2) {
;             PG8_LDB(B0, 0, 0); PG8_LDB(B1, 0, 1); PG8_SCHED; PG8_LDA(At, 0, 0); PG8_STAGE(PG8_SA(1, 1), a1 + hstep, voffA);
;             PG8_WAIT_V(8); PG8_WAIT_L(0); PG8_BAR; PG8_MMA(0, 0, At, B0); PG8_MMA(0, 1, At, B1); PG8_BAR; PG8_SCHED;
;             PG8_LDA(At, 0, 1); PG8_STAGE(PG8_SB(0, 0), b2, voffB); PG8_STAGE(PG8_SB(0, 1), b2 + hstep, voffB); PG8_STAGE(PG8_SA(0, 0), a2, voffA);
;             PG8_WAIT_V(8); PG8_WAIT_L(0); PG8_BAR; PG8_MMA(1, 0, At, B0); PG8_MMA(1, 1, At, B1); PG8_BAR; PG8_SCHED;
.LBB0_428:
	s_add_u32 s20, s18, 0xfffc0080
	s_addc_u32 s21, s19, -1
	s_add_i32 s46, 0, 0x10000
	s_cmp_eq_u32 s45, 12
	s_cselect_b32 s23, s11, s21
	s_cselect_b32 s22, s33, s20
	s_cselect_b32 s21, s9, s44
	s_cselect_b32 s20, s42, s43
	s_add_i32 s48, 0, 0x14000
	v_add_u32_e32 v152, s46, v166
	v_add_u32_e32 v164, s48, v166
	ds_read_b128 v[140:143], v152
	ds_read_b128 v[144:147], v152 offset:1024
	ds_read_b128 v[148:151], v152 offset:2048
	ds_read_b128 v[152:155], v152 offset:3072
	ds_read_b128 v[156:159], v164
	ds_read_b128 v[160:163], v164 offset:1024
	ds_read_b128 v[170:173], v164 offset:2048
	ds_read_b128 v[174:177], v164 offset:3072
	v_lshl_add_u64 v[210:211], s[18:19], 0, v[136:137]
	s_add_i32 m0, s30, 0xc000
	ds_read_b128 v[178:181], v168
	ds_read_b128 v[182:185], v168 offset:1024
	ds_read_b128 v[186:189], v168 offset:2048
	ds_read_b128 v[190:193], v168 offset:3072
	ds_read_b128 v[194:197], v168 offset:4096
	ds_read_b128 v[198:201], v168 offset:5120
	ds_read_b128 v[202:205], v168 offset:6144
	ds_read_b128 v[206:209], v168 offset:7168
	global_load_lds_dwordx4 v[210:211], off
	v_lshl_add_u64 v[210:211], s[18:19], 0, v[138:139]
	s_add_i32 m0, s30, 0xe000
	s_nop 0
	global_load_lds_dwordx4 v[210:211], off
	s_waitcnt vmcnt(8)
	s_waitcnt lgkmcnt(0)
	s_barrier
	s_setprio 1
	s_waitcnt lgkmcnt(0)
	v_mfma_f32_16x16x32_bf16 v[126:129], v[140:143], v[178:181], v[126:129]
	v_mfma_f32_16x16x32_bf16 v[118:121], v[148:151], v[178:181], v[118:121]
	v_mfma_f32_16x16x32_bf16 v[110:113], v[140:143], v[186:189], v[110:113]
	v_mfma_f32_16x16x32_bf16 v[102:105], v[148:151], v[186:189], v[102:105]
	v_mfma_f32_16x16x32_bf16 v[94:97], v[140:143], v[194:197], v[94:97]
	v_mfma_f32_16x16x32_bf16 v[86:89], v[148:151], v[194:197], v[86:89]
	v_mfma_f32_16x16x32_bf16 v[78:81], v[140:143], v[202:205], v[78:81]
	v_mfma_f32_16x16x32_bf16 v[70:73], v[148:151], v[202:205], v[70:73]
	v_mfma_f32_16x16x32_bf16 v[126:129], v[144:147], v[182:185], v[126:129]
	v_mfma_f32_16x16x32_bf16 v[118:121], v[152:155], v[182:185], v[118:121]
	v_mfma_f32_16x16x32_bf16 v[110:113], v[144:147], v[190:193], v[110:113]
	v_mfma_f32_16x16x32_bf16 v[102:105], v[152:155], v[190:193], v[102:105]
	v_mfma_f32_16x16x32_bf16 v[94:97], v[144:147], v[198:201], v[94:97]
	v_mfma_f32_16x16x32_bf16 v[86:89], v[152:155], v[198:201], v[86:89]
	v_mfma_f32_16x16x32_bf16 v[78:81], v[144:147], v[206:209], v[78:81]
	v_mfma_f32_16x16x32_bf16 v[70:73], v[152:155], v[206:209], v[70:73]
	s_setprio 0
	s_setprio 1
	v_mfma_f32_16x16x32_bf16 v[122:125], v[156:159], v[178:181], v[122:125]
	v_mfma_f32_16x16x32_bf16 v[114:117], v[170:173], v[178:181], v[114:117]
	v_mfma_f32_16x16x32_bf16 v[106:109], v[156:159], v[186:189], v[106:109]
	v_mfma_f32_16x16x32_bf16 v[98:101], v[170:173], v[186:189], v[98:101]
	v_mfma_f32_16x16x32_bf16 v[90:93], v[156:159], v[194:197], v[90:93]
	v_mfma_f32_16x16x32_bf16 v[82:85], v[170:173], v[194:197], v[82:85]
	v_mfma_f32_16x16x32_bf16 v[74:77], v[156:159], v[202:205], v[74:77]
	v_mfma_f32_16x16x32_bf16 v[66:69], v[170:173], v[202:205], v[66:69]
	v_mfma_f32_16x16x32_bf16 v[122:125], v[160:163], v[182:185], v[122:125]
	v_mfma_f32_16x16x32_bf16 v[114:117], v[174:177], v[182:185], v[114:117]
	v_mfma_f32_16x16x32_bf16 v[106:109], v[160:163], v[190:193], v[106:109]
	v_mfma_f32_16x16x32_bf16 v[98:101], v[174:177], v[190:193], v[98:101]
	v_mfma_f32_16x16x32_bf16 v[90:93], v[160:163], v[198:201], v[90:93]
	v_mfma_f32_16x16x32_bf16 v[82:85], v[174:177], v[198:201], v[82:85]
	v_mfma_f32_16x16x32_bf16 v[74:77], v[160:163], v[206:209], v[74:77]
	v_mfma_f32_16x16x32_bf16 v[66:69], v[174:177], v[206:209], v[66:69]
	s_setprio 0
	s_barrier
	s_add_i32 s46, s46, s29
	v_lshl_add_u64 v[210:211], s[20:21], 0, v[0:1]
	s_mov_b32 m0, s46
	ds_read_b128 v[178:181], v168 offset:16384
	ds_read_b128 v[182:185], v168 offset:17408
	ds_read_b128 v[186:189], v168 offset:18432
	ds_read_b128 v[190:193], v168 offset:19456
	ds_read_b128 v[194:197], v168 offset:20480
	ds_read_b128 v[198:201], v168 offset:21504
	ds_read_b128 v[202:205], v168 offset:22528
	ds_read_b128 v[206:209], v168 offset:23552
	global_load_lds_dwordx4 v[210:211], off
	s_add_i32 m0, s46, 0x2000
	s_add_u32 s46, s20, 0x40000
	v_lshl_add_u64 v[212:213], s[20:21], 0, v[130:131]
	s_addc_u32 s47, s21, 0
	s_add_i32 s48, s48, s29
	global_load_lds_dwordx4 v[212:213], off
	v_lshl_add_u64 v[214:215], s[46:47], 0, v[0:1]
	s_mov_b32 m0, s48
	v_lshl_add_u64 v[216:217], s[22:23], 0, v[132:133]
	global_load_lds_dwordx4 v[214:215], off
	v_lshl_add_u64 v[214:215], s[46:47], 0, v[130:131]
	s_add_i32 m0, s48, 0x2000
	s_nop 0
	global_load_lds_dwordx4 v[214:215], off
	v_lshl_add_u64 v[214:215], s[22:23], 0, v[134:135]
	s_mov_b32 m0, s30
	s_nop 0
	global_load_lds_dwordx4 v[214:215], off
	s_mov_b32 m0, s31
	s_nop 0
	global_load_lds_dwordx4 v[216:217], off
	s_waitcnt vmcnt(8)
	s_waitcnt lgkmcnt(0)
	s_barrier
; #define PG8_STAGE(bufoff, gbase, voff) do { _Pragma("unroll") for (int _i = 0; _i < 2; ++_i) \
;         __builtin_amdgcn_global_load_lds((const unsigned*)((const char*)(gbase) + (voff)[_i]), (PG8_LAS unsigned*)(lds + (bufoff) + ldsw + _i * 8192), 16, 0, 0); } while (0)
; #define PG8_LDA(dst, b, h) do { _Pragma("unroll") for (int m = 0; m < 4; ++m) _Pragma("unroll") for (int k = 0; k < 2; ++k) dst[m][k] = *(const PG8_LAS bf16x8*)(lds + PG8_SA(b, h) + aoff + m * 2048 + k * 1024); } while (0)
; #define PG8_LDB(dst, b, h) do { _Pragma("unroll") for (int n = 0; n < 2; ++n) _Pragma("unroll") for (int k = 0; k < 2; ++k) dst[n][k] = *(const PG8_LAS bf16x8*)(lds + PG8_SB(b, h) + boff + n * 2048 + k * 1024); } while (0)
; #define PG8_MMA(ai, bj, At, Bt) do { __builtin_amdgcn_s_setprio(1); _Pragma("unroll") for (int m = 0; m < 4; ++m) _Pragma("unroll") for (int n = 0; n < 2; ++n) _Pragma("unroll") for (int k = 0; k < 2; ++k) \
;         acc[ai][bj][m][n] = __builtin_amdgcn_mfma_f32_16x16x32_bf16(Bt[n][k], At[m][k], acc[ai][bj][m][n], 0, 0, 0); __builtin_amdgcn_s_setprio(0); } while (0)
; #define PG8_WAIT_V(n) asm volatile("s_waitcnt vmcnt(" #n ")" ::: "memory")
; #define PG8_WAIT_L(n) asm volatile("s_waitcnt lgkmcnt(" #n ")" ::: "memory")
; #define PG8_BAR __builtin_amdgcn_s_barrier()
; #define PG8_SCHED __builtin_amdgcn_sched_barrier(0)
; template <class Epi, class Sched, bool ALIGN_EPI = false, bool SP2 = false>
; __device__ __forceinline__ void gemm_phase(PG8_LAS unsigned char* lds, const Gemm g, const Sched& S, const Epi& E, const int wv) {
;     ...
;             PG8_WAIT_V(8); PG8_WAIT_L(0); PG8_BAR; PG8_MMA(1, 0, At, B0); PG8_MMA(1, 1, At, B1); PG8_BAR; PG8_SCHED;
;             PG8_LDB(B0, 1, 0); PG8_LDB(B1, 1, 1); PG8_SCHED; PG8_LDA(At, 1, 0); PG8_STAGE(PG8_SA(0, 1), a2 + hstep, voffA);
;             PG8_WAIT_V(8); PG8_WAIT_L(0); PG8_BAR; PG8_MMA(0, 0, At, B0); PG8_MMA(0, 1, At, B1); PG8_BAR; PG8_SCHED;
	s_setprio 1
	s_waitcnt lgkmcnt(0)
	v_mfma_f32_16x16x32_bf16 v[62:65], v[140:143], v[178:181], v[62:65]
	v_mfma_f32_16x16x32_bf16 v[54:57], v[148:151], v[178:181], v[54:57]
	v_mfma_f32_16x16x32_bf16 v[46:49], v[140:143], v[186:189], v[46:49]
	v_mfma_f32_16x16x32_bf16 v[38:41], v[148:151], v[186:189], v[38:41]
	v_mfma_f32_16x16x32_bf16 v[30:33], v[140:143], v[194:197], v[30:33]
	v_mfma_f32_16x16x32_bf16 v[22:25], v[148:151], v[194:197], v[22:25]
	v_mfma_f32_16x16x32_bf16 v[14:17], v[140:143], v[202:205], v[14:17]
	v_mfma_f32_16x16x32_bf16 v[6:9], v[148:151], v[202:205], v[6:9]
	v_mfma_f32_16x16x32_bf16 v[62:65], v[144:147], v[182:185], v[62:65]
	v_mfma_f32_16x16x32_bf16 v[54:57], v[152:155], v[182:185], v[54:57]
	v_mfma_f32_16x16x32_bf16 v[46:49], v[144:147], v[190:193], v[46:49]
	v_mfma_f32_16x16x32_bf16 v[38:41], v[152:155], v[190:193], v[38:41]
	v_mfma_f32_16x16x32_bf16 v[30:33], v[144:147], v[198:201], v[30:33]
	v_mfma_f32_16x16x32_bf16 v[22:25], v[152:155], v[198:201], v[22:25]
	v_mfma_f32_16x16x32_bf16 v[14:17], v[144:147], v[206:209], v[14:17]
	v_mfma_f32_16x16x32_bf16 v[6:9], v[152:155], v[206:209], v[6:9]
	s_setprio 0
	s_setprio 1
	v_mfma_f32_16x16x32_bf16 v[58:61], v[156:159], v[178:181], v[58:61]
	v_mfma_f32_16x16x32_bf16 v[50:53], v[170:173], v[178:181], v[50:53]
	v_mfma_f32_16x16x32_bf16 v[42:45], v[156:159], v[186:189], v[42:45]
	v_mfma_f32_16x16x32_bf16 v[34:37], v[170:173], v[186:189], v[34:37]
	v_mfma_f32_16x16x32_bf16 v[26:29], v[156:159], v[194:197], v[26:29]
	v_mfma_f32_16x16x32_bf16 v[18:21], v[170:173], v[194:197], v[18:21]
	v_mfma_f32_16x16x32_bf16 v[10:13], v[156:159], v[202:205], v[10:13]
	v_mfma_f32_16x16x32_bf16 v[2:5], v[170:173], v[202:205], v[2:5]
	v_mfma_f32_16x16x32_bf16 v[58:61], v[160:163], v[182:185], v[58:61]
	v_mfma_f32_16x16x32_bf16 v[50:53], v[174:177], v[182:185], v[50:53]
	v_mfma_f32_16x16x32_bf16 v[42:45], v[160:163], v[190:193], v[42:45]
	v_mfma_f32_16x16x32_bf16 v[34:37], v[174:177], v[190:193], v[34:37]
	v_mfma_f32_16x16x32_bf16 v[26:29], v[160:163], v[198:201], v[26:29]
	v_mfma_f32_16x16x32_bf16 v[18:21], v[174:177], v[198:201], v[18:21]
	v_mfma_f32_16x16x32_bf16 v[10:13], v[160:163], v[206:209], v[10:13]
	v_mfma_f32_16x16x32_bf16 v[2:5], v[174:177], v[206:209], v[2:5]
	s_setprio 0
	s_barrier
	s_add_i32 s46, 0, 0x18000
	s_add_i32 s47, 0, 0x1c000
	v_add_u32_e32 v152, s46, v166
	v_add_u32_e32 v164, s47, v166
	ds_read_b128 v[140:143], v152
	ds_read_b128 v[144:147], v152 offset:1024
	ds_read_b128 v[148:151], v152 offset:2048
	ds_read_b128 v[152:155], v152 offset:3072
	ds_read_b128 v[156:159], v164
	ds_read_b128 v[160:163], v164 offset:1024
	ds_read_b128 v[170:173], v164 offset:2048
	ds_read_b128 v[174:177], v164 offset:3072
	s_add_u32 s22, s22, 0x40000
	s_addc_u32 s23, s23, 0
	s_mov_b32 m0, s36
	v_lshl_add_u64 v[218:219], s[22:23], 0, v[134:135]
	ds_read_b128 v[178:181], v168 offset:32768
	ds_read_b128 v[182:185], v168 offset:33792
	ds_read_b128 v[186:189], v168 offset:34816
	ds_read_b128 v[190:193], v168 offset:35840
	ds_read_b128 v[194:197], v168 offset:36864
	ds_read_b128 v[198:201], v168 offset:37888
	ds_read_b128 v[202:205], v168 offset:38912
	ds_read_b128 v[206:209], v168 offset:39936
	global_load_lds_dwordx4 v[218:219], off
	v_lshl_add_u64 v[218:219], s[22:23], 0, v[132:133]
	s_mov_b32 m0, s37
	s_nop 0
	global_load_lds_dwordx4 v[218:219], off
	s_waitcnt vmcnt(8)
	s_waitcnt lgkmcnt(0)
	s_barrier
	s_setprio 1
	s_waitcnt lgkmcnt(0)
	v_mfma_f32_16x16x32_bf16 v[126:129], v[140:143], v[178:181], v[126:129]
	v_mfma_f32_16x16x32_bf16 v[118:121], v[148:151], v[178:181], v[118:121]
	v_mfma_f32_16x16x32_bf16 v[110:113], v[140:143], v[186:189], v[110:113]
	v_mfma_f32_16x16x32_bf16 v[102:105], v[148:151], v[186:189], v[102:105]
	v_mfma_f32_16x16x32_bf16 v[94:97], v[140:143], v[194:197], v[94:97]
	v_mfma_f32_16x16x32_bf16 v[86:89], v[148:151], v[194:197], v[86:89]
	v_mfma_f32_16x16x32_bf16 v[78:81], v[140:143], v[202:205], v[78:81]
	v_mfma_f32_16x16x32_bf16 v[70:73], v[148:151], v[202:205], v[70:73]
	v_mfma_f32_16x16x32_bf16 v[126:129], v[144:147], v[182:185], v[126:129]
	v_mfma_f32_16x16x32_bf16 v[118:121], v[152:155], v[182:185], v[118:121]
	v_mfma_f32_16x16x32_bf16 v[110:113], v[144:147], v[190:193], v[110:113]
	v_mfma_f32_16x16x32_bf16 v[102:105], v[152:155], v[190:193], v[102:105]
	v_mfma_f32_16x16x32_bf16 v[94:97], v[144:147], v[198:201], v[94:97]
	v_mfma_f32_16x16x32_bf16 v[86:89], v[152:155], v[198:201], v[86:89]
	v_mfma_f32_16x16x32_bf16 v[78:81], v[144:147], v[206:209], v[78:81]
	v_mfma_f32_16x16x32_bf16 v[70:73], v[152:155], v[206:209], v[70:73]
	s_setprio 0
	s_setprio 1
	v_mfma_f32_16x16x32_bf16 v[122:125], v[156:159], v[178:181], v[122:125]
	v_mfma_f32_16x16x32_bf16 v[114:117], v[170:173], v[178:181], v[114:117]
	v_mfma_f32_16x16x32_bf16 v[106:109], v[156:159], v[186:189], v[106:109]
	v_mfma_f32_16x16x32_bf16 v[98:101], v[170:173], v[186:189], v[98:101]
	v_mfma_f32_16x16x32_bf16 v[90:93], v[156:159], v[194:197], v[90:93]
	v_mfma_f32_16x16x32_bf16 v[82:85], v[170:173], v[194:197], v[82:85]
	v_mfma_f32_16x16x32_bf16 v[74:77], v[156:159], v[202:205], v[74:77]
	v_mfma_f32_16x16x32_bf16 v[66:69], v[170:173], v[202:205], v[66:69]
	v_mfma_f32_16x16x32_bf16 v[122:125], v[160:163], v[182:185], v[122:125]
	v_mfma_f32_16x16x32_bf16 v[114:117], v[174:177], v[182:185], v[114:117]
	v_mfma_f32_16x16x32_bf16 v[106:109], v[160:163], v[190:193], v[106:109]
	v_mfma_f32_16x16x32_bf16 v[98:101], v[174:177], v[190:193], v[98:101]
	v_mfma_f32_16x16x32_bf16 v[90:93], v[160:163], v[198:201], v[90:93]
	v_mfma_f32_16x16x32_bf16 v[82:85], v[174:177], v[198:201], v[82:85]
	v_mfma_f32_16x16x32_bf16 v[74:77], v[160:163], v[206:209], v[74:77]
	v_mfma_f32_16x16x32_bf16 v[66:69], v[174:177], v[206:209], v[66:69]
	s_setprio 0
	s_barrier
; #define PG8_STAGE(bufoff, gbase, voff) do { _Pragma("unroll") for (int _i = 0; _i < 2; ++_i) \
;         __builtin_amdgcn_global_load_lds((const unsigned*)((const char*)(gbase) + (voff)[_i]), (PG8_LAS unsigned*)(lds + (bufoff) + ldsw + _i * 8192), 16, 0, 0); } while (0)
; #define PG8_LDA(dst, b, h) do { _Pragma("unroll") for (int m = 0; m < 4; ++m) _Pragma("unroll") for (int k = 0; k < 2; ++k) dst[m][k] = *(const PG8_LAS bf16x8*)(lds + PG8_SA(b, h) + aoff + m * 2048 + k * 1024); } while (0)
; #define PG8_MMA(ai, bj, At, Bt) do { __builtin_amdgcn_s_setprio(1); _Pragma("unroll") for (int m = 0; m < 4; ++m) _Pragma("unroll") for (int n = 0; n < 2; ++n) _Pragma("unroll") for (int k = 0; k < 2; ++k) \
;         acc[ai][bj][m][n] = __builtin_amdgcn_mfma_f32_16x16x32_bf16(Bt[n][k], At[m][k], acc[ai][bj][m][n], 0, 0, 0); __builtin_amdgcn_s_setprio(0); } while (0)
; #define PG8_WAIT_V(n) asm volatile("s_waitcnt vmcnt(" #n ")" ::: "memory")
; #define PG8_WAIT_L(n) asm volatile("s_waitcnt lgkmcnt(" #n ")" ::: "memory")
; #define PG8_BAR __builtin_amdgcn_s_barrier()
; #define PG8_SCHED __builtin_amdgcn_sched_barrier(0)
; template <class Epi, class Sched, bool ALIGN_EPI = false, bool SP2 = false>
; __device__ __forceinline__ void gemm_phase(PG8_LAS unsigned char* lds, const Gemm g, const Sched& S, const Epi& E, const int wv) {
;     ...
;             PG8_LDA(At, 1, 1); PG8_STAGE(PG8_SB(1, 0), b3, voffB); PG8_STAGE(PG8_SB(1, 1), b3 + hstep, voffB); PG8_STAGE(PG8_SA(1, 0), a3, voffA);
;             PG8_WAIT_V(8); PG8_WAIT_L(0); PG8_BAR; PG8_MMA(1, 0, At, B0); PG8_MMA(1, 1, At, B1); PG8_BAR; PG8_SCHED;
;     ...
;         if constexpr (ALIGN_EPI) { if (wr == 0) PG8_BAR; }
	s_add_i32 s22, s46, s29
	v_lshl_add_u64 v[210:211], v[210:211], 0, s[2:3]
	s_mov_b32 m0, s22
	ds_read_b128 v[178:181], v168 offset:49152
	ds_read_b128 v[182:185], v168 offset:50176
	ds_read_b128 v[186:189], v168 offset:51200
	ds_read_b128 v[190:193], v168 offset:52224
	ds_read_b128 v[194:197], v168 offset:53248
	ds_read_b128 v[198:201], v168 offset:54272
	ds_read_b128 v[202:205], v168 offset:55296
	ds_read_b128 v[206:209], v168 offset:56320
	global_load_lds_dwordx4 v[210:211], off
	s_add_i32 m0, s22, 0x2000
	s_add_u32 s20, s20, 0x40080
	v_lshl_add_u64 v[210:211], v[212:213], 0, s[2:3]
	s_addc_u32 s21, s21, 0
	s_add_i32 s22, s47, s29
	global_load_lds_dwordx4 v[210:211], off
	v_lshl_add_u64 v[210:211], s[20:21], 0, v[0:1]
	s_mov_b32 m0, s22
	s_nop 0
	global_load_lds_dwordx4 v[210:211], off
	v_lshl_add_u64 v[210:211], s[20:21], 0, v[130:131]
	s_add_i32 m0, s22, 0x2000
	s_nop 0
	global_load_lds_dwordx4 v[210:211], off
	v_lshl_add_u64 v[210:211], v[214:215], 0, s[2:3]
	s_mov_b32 m0, s39
	s_nop 0
	global_load_lds_dwordx4 v[210:211], off
	v_lshl_add_u64 v[210:211], v[216:217], 0, s[2:3]
	s_mov_b32 m0, s40
	s_nop 0
	global_load_lds_dwordx4 v[210:211], off
	s_waitcnt vmcnt(8)
	s_waitcnt lgkmcnt(0)
	s_barrier
	s_setprio 1
	s_waitcnt lgkmcnt(0)
	v_mfma_f32_16x16x32_bf16 v[62:65], v[140:143], v[178:181], v[62:65]
	v_mfma_f32_16x16x32_bf16 v[54:57], v[148:151], v[178:181], v[54:57]
	v_mfma_f32_16x16x32_bf16 v[46:49], v[140:143], v[186:189], v[46:49]
	v_mfma_f32_16x16x32_bf16 v[38:41], v[148:151], v[186:189], v[38:41]
	v_mfma_f32_16x16x32_bf16 v[30:33], v[140:143], v[194:197], v[30:33]
	v_mfma_f32_16x16x32_bf16 v[22:25], v[148:151], v[194:197], v[22:25]
	v_mfma_f32_16x16x32_bf16 v[14:17], v[140:143], v[202:205], v[14:17]
	v_mfma_f32_16x16x32_bf16 v[6:9], v[148:151], v[202:205], v[6:9]
	v_mfma_f32_16x16x32_bf16 v[62:65], v[144:147], v[182:185], v[62:65]
	v_mfma_f32_16x16x32_bf16 v[54:57], v[152:155], v[182:185], v[54:57]
	v_mfma_f32_16x16x32_bf16 v[46:49], v[144:147], v[190:193], v[46:49]
	v_mfma_f32_16x16x32_bf16 v[38:41], v[152:155], v[190:193], v[38:41]
	v_mfma_f32_16x16x32_bf16 v[30:33], v[144:147], v[198:201], v[30:33]
	v_mfma_f32_16x16x32_bf16 v[22:25], v[152:155], v[198:201], v[22:25]
	v_mfma_f32_16x16x32_bf16 v[14:17], v[144:147], v[206:209], v[14:17]
	v_mfma_f32_16x16x32_bf16 v[6:9], v[152:155], v[206:209], v[6:9]
	s_setprio 0
	s_setprio 1
	v_mfma_f32_16x16x32_bf16 v[58:61], v[156:159], v[178:181], v[58:61]
	v_mfma_f32_16x16x32_bf16 v[50:53], v[170:173], v[178:181], v[50:53]
	v_mfma_f32_16x16x32_bf16 v[42:45], v[156:159], v[186:189], v[42:45]
	v_mfma_f32_16x16x32_bf16 v[34:37], v[170:173], v[186:189], v[34:37]
	v_mfma_f32_16x16x32_bf16 v[26:29], v[156:159], v[194:197], v[26:29]
	v_mfma_f32_16x16x32_bf16 v[18:21], v[170:173], v[194:197], v[18:21]
	v_mfma_f32_16x16x32_bf16 v[10:13], v[156:159], v[202:205], v[10:13]
	v_mfma_f32_16x16x32_bf16 v[2:5], v[170:173], v[202:205], v[2:5]
	v_mfma_f32_16x16x32_bf16 v[58:61], v[160:163], v[182:185], v[58:61]
	v_mfma_f32_16x16x32_bf16 v[50:53], v[174:177], v[182:185], v[50:53]
	v_mfma_f32_16x16x32_bf16 v[42:45], v[160:163], v[190:193], v[42:45]
	v_mfma_f32_16x16x32_bf16 v[34:37], v[174:177], v[190:193], v[34:37]
	v_mfma_f32_16x16x32_bf16 v[26:29], v[160:163], v[198:201], v[26:29]
	v_mfma_f32_16x16x32_bf16 v[18:21], v[174:177], v[198:201], v[18:21]
	v_mfma_f32_16x16x32_bf16 v[10:13], v[160:163], v[206:209], v[10:13]
	v_mfma_f32_16x16x32_bf16 v[2:5], v[174:177], v[206:209], v[2:5]
	s_setprio 0
	s_add_i32 s45, s45, 2
	s_add_u32 s18, s18, 0x100
	s_addc_u32 s19, s19, 0
	s_add_u32 s43, s43, 0x100
	s_addc_u32 s44, s44, 0
	s_cmp_gt_u32 s45, 13
	s_barrier
	s_cbranch_scc0 .LBB0_428
	s_and_b64 vcc, exec, s[6:7]
	s_cbranch_vccz .LBB0_431
	s_barrier

; #define PG8_STAGE(bufoff, gbase, voff) do { _Pragma("unroll") for (int _i = 0; _i < 2; ++_i) \
;         __builtin_amdgcn_global_load_lds((const unsigned*)((const char*)(gbase) + (voff)[_i]), (PG8_LAS unsigned*)(lds + (bufoff) + ldsw + _i * 8192), 16, 0, 0); } while (0)
; #define PG8_LDA(dst, b, h) do { _Pragma("unroll") for (int m = 0; m < 4; ++m) _Pragma("unroll") for (int k = 0; k < 2; ++k) dst[m][k] = *(const PG8_LAS bf16x8*)(lds + PG8_SA(b, h) + aoff + m * 2048 + k * 1024); } while (0)
; #define PG8_LDB(dst, b, h) do { _Pragma("unroll") for (int n = 0; n < 2; ++n) _Pragma("unroll") for (int k = 0; k < 2; ++k) dst[n][k] = *(const PG8_LAS bf16x8*)(lds + PG8_SB(b, h) + boff + n * 2048 + k * 1024); } while (0)
; #define PG8_MMA(ai, bj, At, Bt) do { __builtin_amdgcn_s_setprio(1); _Pragma("unroll") for (int m = 0; m < 4; ++m) _Pragma("unroll") for (int n = 0; n < 2; ++n) _Pragma("unroll") for (int k = 0; k < 2; ++k) \
;         acc[ai][bj][m][n] = __builtin_amdgcn_mfma_f32_16x16x32_bf16(Bt[n][k], At[m][k], acc[ai][bj][m][n], 0, 0, 0); __builtin_amdgcn_s_setprio(0); } while (0)
; #define PG8_WAIT_V(n) asm volatile("s_waitcnt vmcnt(" #n ")" ::: "memory")
; #define PG8_WAIT_L(n) asm volatile("s_waitcnt lgkmcnt(" #n ")" ::: "memory")
; template <class Epi, class Sched, bool ALIGN_EPI = false, bool SP2 = false>
; __device__ __forceinline__ void gemm_phase(PG8_LAS unsigned char* lds, const Gemm g, const Sched& S, const Epi& E, const int wv) {
;     ...
;             const bool last = (t == nt - 2);
;             const char* a1 = cA + (size_t)(t + 1) * kstep;
;             const char* a2 = last ? nA : cA + (size_t)(t + 2) * kstep; const char* b2 = last ? nB : cB + (size_t)(t + 2) * kstep;
;             const char* a3 = a2 + kstep; const char* b3 = b2 + kstep;
;             if (last && has_next) S.a_ready(nxt);
;             if constexpr (SP2) {
;             PG8_LDB(B0, 0, 0); PG8_LDB(B1, 0, 1); PG8_SCHED; PG8_LDA(At, 0, 0); PG8_STAGE(PG8_SA(1, 1), a1 + hstep, voffA);
;             PG8_WAIT_V(8); PG8_WAIT_L(0); PG8_BAR; PG8_MMA(0, 0, At, B0); PG8_MMA(0, 1, At, B1); PG8_BAR; PG8_SCHED;
;             PG8_LDA(At, 0, 1); PG8_STAGE(PG8_SB(0, 0), b2, voffB); PG8_STAGE(PG8_SB(0, 1), b2 + hstep, voffB); PG8_STAGE(PG8_SA(0, 0), a2, voffA);
;             PG8_WAIT_V(8); PG8_WAIT_L(0); PG8_BAR; PG8_MMA(1, 0, At, B0); PG8_MMA(1, 1, At, B1); PG8_BAR; PG8_SCHED;
.LBB0_504:
	s_add_u32 s10, s8, 0x100
	s_addc_u32 s11, s9, 0
	s_add_i32 s52, 0, 0x10000
	s_cmp_eq_u32 s51, 40
	s_cselect_b32 s29, s1, s11
	s_cselect_b32 s28, s0, s10
	s_cselect_b32 s27, s25, s50
	s_cselect_b32 s26, s24, s49
	s_add_i32 s53, 0, 0x14000
	v_add_u32_e32 v142, s52, v187
	v_add_u32_e32 v168, s53, v187
	ds_read_b128 v[122:125], v142
	ds_read_b128 v[130:133], v142 offset:1024
	ds_read_b128 v[138:141], v142 offset:2048
	ds_read_b128 v[142:145], v142 offset:3072
	ds_read_b128 v[146:149], v168
	ds_read_b128 v[150:153], v168 offset:1024
	ds_read_b128 v[154:157], v168 offset:2048
	ds_read_b128 v[168:171], v168 offset:3072
	v_lshl_add_u64 v[184:185], s[8:9], 0, v[164:165]
	s_add_i32 m0, s37, 0xc000
	ds_read_b128 v[172:175], v189
	ds_read_b128 v[176:179], v189 offset:1024
	ds_read_b128 v[180:183], v189 offset:2048
	ds_read_b128 v[190:193], v189 offset:3072
	ds_read_b128 v[194:197], v189 offset:4096
	ds_read_b128 v[198:201], v189 offset:5120
	ds_read_b128 v[202:205], v189 offset:6144
	ds_read_b128 v[206:209], v189 offset:7168
	global_load_lds_dwordx4 v[184:185], off
	v_lshl_add_u64 v[184:185], s[8:9], 0, v[166:167]
	s_add_i32 m0, s37, 0xe000
	s_nop 0
	global_load_lds_dwordx4 v[184:185], off
	s_waitcnt vmcnt(8)
	s_waitcnt lgkmcnt(0)
	s_barrier
	s_setprio 1
	s_waitcnt lgkmcnt(0)
	v_mfma_f32_16x16x32_bf16 v[134:137], v[122:125], v[172:175], v[134:137]
	v_mfma_f32_16x16x32_bf16 v[126:129], v[138:141], v[172:175], v[126:129]
	v_mfma_f32_16x16x32_bf16 v[110:113], v[122:125], v[180:183], v[110:113]
	v_mfma_f32_16x16x32_bf16 v[106:109], v[138:141], v[180:183], v[106:109]
	v_mfma_f32_16x16x32_bf16 v[94:97], v[122:125], v[194:197], v[94:97]
	v_mfma_f32_16x16x32_bf16 v[90:93], v[138:141], v[194:197], v[90:93]
	v_mfma_f32_16x16x32_bf16 v[78:81], v[122:125], v[202:205], v[78:81]
	v_mfma_f32_16x16x32_bf16 v[74:77], v[138:141], v[202:205], v[74:77]
	v_mfma_f32_16x16x32_bf16 v[134:137], v[130:133], v[176:179], v[134:137]
	v_mfma_f32_16x16x32_bf16 v[126:129], v[142:145], v[176:179], v[126:129]
	v_mfma_f32_16x16x32_bf16 v[110:113], v[130:133], v[190:193], v[110:113]
	v_mfma_f32_16x16x32_bf16 v[106:109], v[142:145], v[190:193], v[106:109]
	v_mfma_f32_16x16x32_bf16 v[94:97], v[130:133], v[198:201], v[94:97]
	v_mfma_f32_16x16x32_bf16 v[90:93], v[142:145], v[198:201], v[90:93]
	v_mfma_f32_16x16x32_bf16 v[78:81], v[130:133], v[206:209], v[78:81]
	v_mfma_f32_16x16x32_bf16 v[74:77], v[142:145], v[206:209], v[74:77]
	s_setprio 0
	s_setprio 1
	v_mfma_f32_16x16x32_bf16 v[118:121], v[146:149], v[172:175], v[118:121]
	v_mfma_f32_16x16x32_bf16 v[114:117], v[154:157], v[172:175], v[114:117]
	v_mfma_f32_16x16x32_bf16 v[102:105], v[146:149], v[180:183], v[102:105]
	v_mfma_f32_16x16x32_bf16 v[98:101], v[154:157], v[180:183], v[98:101]
	v_mfma_f32_16x16x32_bf16 v[86:89], v[146:149], v[194:197], v[86:89]
	v_mfma_f32_16x16x32_bf16 v[82:85], v[154:157], v[194:197], v[82:85]
	v_mfma_f32_16x16x32_bf16 v[70:73], v[146:149], v[202:205], v[70:73]
	v_mfma_f32_16x16x32_bf16 v[66:69], v[154:157], v[202:205], v[66:69]
	v_mfma_f32_16x16x32_bf16 v[118:121], v[150:153], v[176:179], v[118:121]
	v_mfma_f32_16x16x32_bf16 v[114:117], v[168:171], v[176:179], v[114:117]
	v_mfma_f32_16x16x32_bf16 v[102:105], v[150:153], v[190:193], v[102:105]
	v_mfma_f32_16x16x32_bf16 v[98:101], v[168:171], v[190:193], v[98:101]
	v_mfma_f32_16x16x32_bf16 v[86:89], v[150:153], v[198:201], v[86:89]
	v_mfma_f32_16x16x32_bf16 v[82:85], v[168:171], v[198:201], v[82:85]
	v_mfma_f32_16x16x32_bf16 v[70:73], v[150:153], v[206:209], v[70:73]
	v_mfma_f32_16x16x32_bf16 v[66:69], v[168:171], v[206:209], v[66:69]
	s_setprio 0
	s_barrier
	s_add_i32 s8, s52, s36
	v_lshl_add_u64 v[184:185], s[26:27], 0, v[0:1]
	s_mov_b32 m0, s8
	ds_read_b128 v[172:175], v189 offset:16384
	ds_read_b128 v[176:179], v189 offset:17408
	ds_read_b128 v[180:183], v189 offset:18432
	ds_read_b128 v[190:193], v189 offset:19456
	ds_read_b128 v[194:197], v189 offset:20480
	ds_read_b128 v[198:201], v189 offset:21504
	ds_read_b128 v[202:205], v189 offset:22528
	ds_read_b128 v[206:209], v189 offset:23552
	global_load_lds_dwordx4 v[184:185], off
	s_add_i32 m0, s8, 0x2000
	s_add_u32 s8, s26, 0xb0000
	v_lshl_add_u64 v[210:211], s[26:27], 0, v[162:163]
	s_addc_u32 s9, s27, 0
	s_add_i32 s52, s53, s36
	global_load_lds_dwordx4 v[210:211], off
	v_lshl_add_u64 v[212:213], s[8:9], 0, v[0:1]
	s_mov_b32 m0, s52
	v_lshl_add_u64 v[214:215], s[28:29], 0, v[160:161]
	global_load_lds_dwordx4 v[212:213], off
	v_lshl_add_u64 v[212:213], s[8:9], 0, v[162:163]
	s_add_i32 m0, s52, 0x2000
	s_nop 0
	global_load_lds_dwordx4 v[212:213], off
	v_lshl_add_u64 v[212:213], s[28:29], 0, v[158:159]
	s_mov_b32 m0, s37
	s_nop 0
	global_load_lds_dwordx4 v[212:213], off
	s_mov_b32 m0, s38
	s_nop 0
	global_load_lds_dwordx4 v[214:215], off
	s_waitcnt vmcnt(8)
	s_waitcnt lgkmcnt(0)
	s_barrier
; #define PG8_STAGE(bufoff, gbase, voff) do { _Pragma("unroll") for (int _i = 0; _i < 2; ++_i) \
;         __builtin_amdgcn_global_load_lds((const unsigned*)((const char*)(gbase) + (voff)[_i]), (PG8_LAS unsigned*)(lds + (bufoff) + ldsw + _i * 8192), 16, 0, 0); } while (0)
; #define PG8_LDA(dst, b, h) do { _Pragma("unroll") for (int m = 0; m < 4; ++m) _Pragma("unroll") for (int k = 0; k < 2; ++k) dst[m][k] = *(const PG8_LAS bf16x8*)(lds + PG8_SA(b, h) + aoff + m * 2048 + k * 1024); } while (0)
; #define PG8_LDB(dst, b, h) do { _Pragma("unroll") for (int n = 0; n < 2; ++n) _Pragma("unroll") for (int k = 0; k < 2; ++k) dst[n][k] = *(const PG8_LAS bf16x8*)(lds + PG8_SB(b, h) + boff + n * 2048 + k * 1024); } while (0)
; #define PG8_MMA(ai, bj, At, Bt) do { __builtin_amdgcn_s_setprio(1); _Pragma("unroll") for (int m = 0; m < 4; ++m) _Pragma("unroll") for (int n = 0; n < 2; ++n) _Pragma("unroll") for (int k = 0; k < 2; ++k) \
;         acc[ai][bj][m][n] = __builtin_amdgcn_mfma_f32_16x16x32_bf16(Bt[n][k], At[m][k], acc[ai][bj][m][n], 0, 0, 0); __builtin_amdgcn_s_setprio(0); } while (0)
; #define PG8_WAIT_V(n) asm volatile("s_waitcnt vmcnt(" #n ")" ::: "memory")
; #define PG8_WAIT_L(n) asm volatile("s_waitcnt lgkmcnt(" #n ")" ::: "memory")
; #define PG8_BAR __builtin_amdgcn_s_barrier()
; #define PG8_SCHED __builtin_amdgcn_sched_barrier(0)
; template <class Epi, class Sched, bool ALIGN_EPI = false, bool SP2 = false>
; __device__ __forceinline__ void gemm_phase(PG8_LAS unsigned char* lds, const Gemm g, const Sched& S, const Epi& E, const int wv) {
;     ...
;             PG8_WAIT_V(8); PG8_WAIT_L(0); PG8_BAR; PG8_MMA(1, 0, At, B0); PG8_MMA(1, 1, At, B1); PG8_BAR; PG8_SCHED;
;             PG8_LDB(B0, 1, 0); PG8_LDB(B1, 1, 1); PG8_SCHED; PG8_LDA(At, 1, 0); PG8_STAGE(PG8_SA(0, 1), a2 + hstep, voffA);
;             PG8_WAIT_V(8); PG8_WAIT_L(0); PG8_BAR; PG8_MMA(0, 0, At, B0); PG8_MMA(0, 1, At, B1); PG8_BAR; PG8_SCHED;
	s_setprio 1
	s_waitcnt lgkmcnt(0)
	v_mfma_f32_16x16x32_bf16 v[62:65], v[122:125], v[172:175], v[62:65]
	v_mfma_f32_16x16x32_bf16 v[58:61], v[138:141], v[172:175], v[58:61]
	v_mfma_f32_16x16x32_bf16 v[46:49], v[122:125], v[180:183], v[46:49]
	v_mfma_f32_16x16x32_bf16 v[42:45], v[138:141], v[180:183], v[42:45]
	v_mfma_f32_16x16x32_bf16 v[30:33], v[122:125], v[194:197], v[30:33]
	v_mfma_f32_16x16x32_bf16 v[26:29], v[138:141], v[194:197], v[26:29]
	v_mfma_f32_16x16x32_bf16 v[14:17], v[122:125], v[202:205], v[14:17]
	v_mfma_f32_16x16x32_bf16 v[10:13], v[138:141], v[202:205], v[10:13]
	v_mfma_f32_16x16x32_bf16 v[62:65], v[130:133], v[176:179], v[62:65]
	v_mfma_f32_16x16x32_bf16 v[58:61], v[142:145], v[176:179], v[58:61]
	v_mfma_f32_16x16x32_bf16 v[46:49], v[130:133], v[190:193], v[46:49]
	v_mfma_f32_16x16x32_bf16 v[42:45], v[142:145], v[190:193], v[42:45]
	v_mfma_f32_16x16x32_bf16 v[30:33], v[130:133], v[198:201], v[30:33]
	v_mfma_f32_16x16x32_bf16 v[26:29], v[142:145], v[198:201], v[26:29]
	v_mfma_f32_16x16x32_bf16 v[14:17], v[130:133], v[206:209], v[14:17]
	v_mfma_f32_16x16x32_bf16 v[10:13], v[142:145], v[206:209], v[10:13]
	s_setprio 0
	s_setprio 1
	v_mfma_f32_16x16x32_bf16 v[54:57], v[146:149], v[172:175], v[54:57]
	v_mfma_f32_16x16x32_bf16 v[50:53], v[154:157], v[172:175], v[50:53]
	v_mfma_f32_16x16x32_bf16 v[38:41], v[146:149], v[180:183], v[38:41]
	v_mfma_f32_16x16x32_bf16 v[34:37], v[154:157], v[180:183], v[34:37]
	v_mfma_f32_16x16x32_bf16 v[22:25], v[146:149], v[194:197], v[22:25]
	v_mfma_f32_16x16x32_bf16 v[18:21], v[154:157], v[194:197], v[18:21]
	v_mfma_f32_16x16x32_bf16 v[6:9], v[146:149], v[202:205], v[6:9]
	v_mfma_f32_16x16x32_bf16 v[2:5], v[154:157], v[202:205], v[2:5]
	v_mfma_f32_16x16x32_bf16 v[54:57], v[150:153], v[176:179], v[54:57]
	v_mfma_f32_16x16x32_bf16 v[50:53], v[168:171], v[176:179], v[50:53]
	v_mfma_f32_16x16x32_bf16 v[38:41], v[150:153], v[190:193], v[38:41]
	v_mfma_f32_16x16x32_bf16 v[34:37], v[168:171], v[190:193], v[34:37]
	v_mfma_f32_16x16x32_bf16 v[22:25], v[150:153], v[198:201], v[22:25]
	v_mfma_f32_16x16x32_bf16 v[18:21], v[168:171], v[198:201], v[18:21]
	v_mfma_f32_16x16x32_bf16 v[6:9], v[150:153], v[206:209], v[6:9]
	v_mfma_f32_16x16x32_bf16 v[2:5], v[168:171], v[206:209], v[2:5]
	s_setprio 0
	s_barrier
	s_add_i32 s52, 0, 0x18000
	s_add_i32 s53, 0, 0x1c000
	v_add_u32_e32 v142, s52, v187
	v_add_u32_e32 v168, s53, v187
	ds_read_b128 v[122:125], v142
	ds_read_b128 v[130:133], v142 offset:1024
	ds_read_b128 v[138:141], v142 offset:2048
	ds_read_b128 v[142:145], v142 offset:3072
	ds_read_b128 v[146:149], v168
	ds_read_b128 v[150:153], v168 offset:1024
	ds_read_b128 v[154:157], v168 offset:2048
	ds_read_b128 v[168:171], v168 offset:3072
	s_add_u32 s8, s28, 0xb0000
	s_addc_u32 s9, s29, 0
	s_mov_b32 m0, s39
	v_lshl_add_u64 v[216:217], s[8:9], 0, v[158:159]
	ds_read_b128 v[172:175], v189 offset:32768
	ds_read_b128 v[176:179], v189 offset:33792
	ds_read_b128 v[180:183], v189 offset:34816
	ds_read_b128 v[190:193], v189 offset:35840
	ds_read_b128 v[194:197], v189 offset:36864
	ds_read_b128 v[198:201], v189 offset:37888
	ds_read_b128 v[202:205], v189 offset:38912
	ds_read_b128 v[206:209], v189 offset:39936
	global_load_lds_dwordx4 v[216:217], off
	v_lshl_add_u64 v[216:217], s[8:9], 0, v[160:161]
	s_mov_b32 m0, s40
	s_nop 0
	global_load_lds_dwordx4 v[216:217], off
	s_waitcnt vmcnt(8)
	s_waitcnt lgkmcnt(0)
	s_barrier
	s_setprio 1
	s_waitcnt lgkmcnt(0)
	v_mfma_f32_16x16x32_bf16 v[134:137], v[122:125], v[172:175], v[134:137]
	v_mfma_f32_16x16x32_bf16 v[126:129], v[138:141], v[172:175], v[126:129]
	v_mfma_f32_16x16x32_bf16 v[110:113], v[122:125], v[180:183], v[110:113]
	v_mfma_f32_16x16x32_bf16 v[106:109], v[138:141], v[180:183], v[106:109]
	v_mfma_f32_16x16x32_bf16 v[94:97], v[122:125], v[194:197], v[94:97]
	v_mfma_f32_16x16x32_bf16 v[90:93], v[138:141], v[194:197], v[90:93]
	v_mfma_f32_16x16x32_bf16 v[78:81], v[122:125], v[202:205], v[78:81]
	v_mfma_f32_16x16x32_bf16 v[74:77], v[138:141], v[202:205], v[74:77]
	v_mfma_f32_16x16x32_bf16 v[134:137], v[130:133], v[176:179], v[134:137]
	v_mfma_f32_16x16x32_bf16 v[126:129], v[142:145], v[176:179], v[126:129]
	v_mfma_f32_16x16x32_bf16 v[110:113], v[130:133], v[190:193], v[110:113]
	v_mfma_f32_16x16x32_bf16 v[106:109], v[142:145], v[190:193], v[106:109]
	v_mfma_f32_16x16x32_bf16 v[94:97], v[130:133], v[198:201], v[94:97]
	v_mfma_f32_16x16x32_bf16 v[90:93], v[142:145], v[198:201], v[90:93]
	v_mfma_f32_16x16x32_bf16 v[78:81], v[130:133], v[206:209], v[78:81]
	v_mfma_f32_16x16x32_bf16 v[74:77], v[142:145], v[206:209], v[74:77]
	s_setprio 0
	s_setprio 1
	v_mfma_f32_16x16x32_bf16 v[118:121], v[146:149], v[172:175], v[118:121]
	v_mfma_f32_16x16x32_bf16 v[114:117], v[154:157], v[172:175], v[114:117]
	v_mfma_f32_16x16x32_bf16 v[102:105], v[146:149], v[180:183], v[102:105]
	v_mfma_f32_16x16x32_bf16 v[98:101], v[154:157], v[180:183], v[98:101]
	v_mfma_f32_16x16x32_bf16 v[86:89], v[146:149], v[194:197], v[86:89]
	v_mfma_f32_16x16x32_bf16 v[82:85], v[154:157], v[194:197], v[82:85]
	v_mfma_f32_16x16x32_bf16 v[70:73], v[146:149], v[202:205], v[70:73]
	v_mfma_f32_16x16x32_bf16 v[66:69], v[154:157], v[202:205], v[66:69]
	v_mfma_f32_16x16x32_bf16 v[118:121], v[150:153], v[176:179], v[118:121]
	v_mfma_f32_16x16x32_bf16 v[114:117], v[168:171], v[176:179], v[114:117]
	v_mfma_f32_16x16x32_bf16 v[102:105], v[150:153], v[190:193], v[102:105]
	v_mfma_f32_16x16x32_bf16 v[98:101], v[168:171], v[190:193], v[98:101]
	v_mfma_f32_16x16x32_bf16 v[86:89], v[150:153], v[198:201], v[86:89]
	v_mfma_f32_16x16x32_bf16 v[82:85], v[168:171], v[198:201], v[82:85]
	v_mfma_f32_16x16x32_bf16 v[70:73], v[150:153], v[206:209], v[70:73]
	v_mfma_f32_16x16x32_bf16 v[66:69], v[168:171], v[206:209], v[66:69]
	s_setprio 0
	s_barrier
; #define PG8_STAGE(bufoff, gbase, voff) do { _Pragma("unroll") for (int _i = 0; _i < 2; ++_i) \
;         __builtin_amdgcn_global_load_lds((const unsigned*)((const char*)(gbase) + (voff)[_i]), (PG8_LAS unsigned*)(lds + (bufoff) + ldsw + _i * 8192), 16, 0, 0); } while (0)
; #define PG8_LDA(dst, b, h) do { _Pragma("unroll") for (int m = 0; m < 4; ++m) _Pragma("unroll") for (int k = 0; k < 2; ++k) dst[m][k] = *(const PG8_LAS bf16x8*)(lds + PG8_SA(b, h) + aoff + m * 2048 + k * 1024); } while (0)
; #define PG8_MMA(ai, bj, At, Bt) do { __builtin_amdgcn_s_setprio(1); _Pragma("unroll") for (int m = 0; m < 4; ++m) _Pragma("unroll") for (int n = 0; n < 2; ++n) _Pragma("unroll") for (int k = 0; k < 2; ++k) \
;         acc[ai][bj][m][n] = __builtin_amdgcn_mfma_f32_16x16x32_bf16(Bt[n][k], At[m][k], acc[ai][bj][m][n], 0, 0, 0); __builtin_amdgcn_s_setprio(0); } while (0)
; #define PG8_WAIT_V(n) asm volatile("s_waitcnt vmcnt(" #n ")" ::: "memory")
; #define PG8_WAIT_L(n) asm volatile("s_waitcnt lgkmcnt(" #n ")" ::: "memory")
; #define PG8_BAR __builtin_amdgcn_s_barrier()
; #define PG8_SCHED __builtin_amdgcn_sched_barrier(0)
; template <class Epi, class Sched, bool ALIGN_EPI = false, bool SP2 = false>
; __device__ __forceinline__ void gemm_phase(PG8_LAS unsigned char* lds, const Gemm g, const Sched& S, const Epi& E, const int wv) {
;     ...
;             PG8_LDA(At, 1, 1); PG8_STAGE(PG8_SB(1, 0), b3, voffB); PG8_STAGE(PG8_SB(1, 1), b3 + hstep, voffB); PG8_STAGE(PG8_SA(1, 0), a3, voffA);
;             PG8_WAIT_V(8); PG8_WAIT_L(0); PG8_BAR; PG8_MMA(1, 0, At, B0); PG8_MMA(1, 1, At, B1); PG8_BAR; PG8_SCHED;
;     ...
;         if constexpr (ALIGN_EPI) { if (wr == 0) PG8_BAR; }
	s_add_i32 s8, s52, s36
	v_lshl_add_u64 v[184:185], v[184:185], 0, s[2:3]
	s_mov_b32 m0, s8
	ds_read_b128 v[172:175], v189 offset:49152
	ds_read_b128 v[176:179], v189 offset:50176
	ds_read_b128 v[180:183], v189 offset:51200
	ds_read_b128 v[190:193], v189 offset:52224
	ds_read_b128 v[194:197], v189 offset:53248
	ds_read_b128 v[198:201], v189 offset:54272
	ds_read_b128 v[202:205], v189 offset:55296
	ds_read_b128 v[206:209], v189 offset:56320
	global_load_lds_dwordx4 v[184:185], off
	s_add_i32 m0, s8, 0x2000
	s_add_u32 s8, s26, 0xb0080
	v_lshl_add_u64 v[184:185], v[210:211], 0, s[2:3]
	s_addc_u32 s9, s27, 0
	s_add_i32 s26, s53, s36
	global_load_lds_dwordx4 v[184:185], off
	v_lshl_add_u64 v[184:185], s[8:9], 0, v[0:1]
	s_mov_b32 m0, s26
	s_nop 0
	global_load_lds_dwordx4 v[184:185], off
	v_lshl_add_u64 v[184:185], s[8:9], 0, v[162:163]
	s_add_i32 m0, s26, 0x2000
	s_nop 0
	global_load_lds_dwordx4 v[184:185], off
	v_lshl_add_u64 v[184:185], v[212:213], 0, s[2:3]
	s_mov_b32 m0, s42
	s_nop 0
	global_load_lds_dwordx4 v[184:185], off
	v_lshl_add_u64 v[184:185], v[214:215], 0, s[2:3]
	s_mov_b32 m0, s43
	s_nop 0
	global_load_lds_dwordx4 v[184:185], off
	s_waitcnt vmcnt(8)
	s_waitcnt lgkmcnt(0)
	s_barrier
	s_setprio 1
	s_waitcnt lgkmcnt(0)
	v_mfma_f32_16x16x32_bf16 v[62:65], v[122:125], v[172:175], v[62:65]
	v_mfma_f32_16x16x32_bf16 v[58:61], v[138:141], v[172:175], v[58:61]
	v_mfma_f32_16x16x32_bf16 v[46:49], v[122:125], v[180:183], v[46:49]
	v_mfma_f32_16x16x32_bf16 v[42:45], v[138:141], v[180:183], v[42:45]
	v_mfma_f32_16x16x32_bf16 v[30:33], v[122:125], v[194:197], v[30:33]
	v_mfma_f32_16x16x32_bf16 v[26:29], v[138:141], v[194:197], v[26:29]
	v_mfma_f32_16x16x32_bf16 v[14:17], v[122:125], v[202:205], v[14:17]
	v_mfma_f32_16x16x32_bf16 v[10:13], v[138:141], v[202:205], v[10:13]
	v_mfma_f32_16x16x32_bf16 v[62:65], v[130:133], v[176:179], v[62:65]
	v_mfma_f32_16x16x32_bf16 v[58:61], v[142:145], v[176:179], v[58:61]
	v_mfma_f32_16x16x32_bf16 v[46:49], v[130:133], v[190:193], v[46:49]
	v_mfma_f32_16x16x32_bf16 v[42:45], v[142:145], v[190:193], v[42:45]
	v_mfma_f32_16x16x32_bf16 v[30:33], v[130:133], v[198:201], v[30:33]
	v_mfma_f32_16x16x32_bf16 v[26:29], v[142:145], v[198:201], v[26:29]
	v_mfma_f32_16x16x32_bf16 v[14:17], v[130:133], v[206:209], v[14:17]
	v_mfma_f32_16x16x32_bf16 v[10:13], v[142:145], v[206:209], v[10:13]
	s_setprio 0
	s_setprio 1
	v_mfma_f32_16x16x32_bf16 v[54:57], v[146:149], v[172:175], v[54:57]
	v_mfma_f32_16x16x32_bf16 v[50:53], v[154:157], v[172:175], v[50:53]
	v_mfma_f32_16x16x32_bf16 v[38:41], v[146:149], v[180:183], v[38:41]
	v_mfma_f32_16x16x32_bf16 v[34:37], v[154:157], v[180:183], v[34:37]
	v_mfma_f32_16x16x32_bf16 v[22:25], v[146:149], v[194:197], v[22:25]
	v_mfma_f32_16x16x32_bf16 v[18:21], v[154:157], v[194:197], v[18:21]
	v_mfma_f32_16x16x32_bf16 v[6:9], v[146:149], v[202:205], v[6:9]
	v_mfma_f32_16x16x32_bf16 v[2:5], v[154:157], v[202:205], v[2:5]
	v_mfma_f32_16x16x32_bf16 v[54:57], v[150:153], v[176:179], v[54:57]
	v_mfma_f32_16x16x32_bf16 v[50:53], v[168:171], v[176:179], v[50:53]
	v_mfma_f32_16x16x32_bf16 v[38:41], v[150:153], v[190:193], v[38:41]
	v_mfma_f32_16x16x32_bf16 v[34:37], v[168:171], v[190:193], v[34:37]
	v_mfma_f32_16x16x32_bf16 v[22:25], v[150:153], v[198:201], v[22:25]
	v_mfma_f32_16x16x32_bf16 v[18:21], v[168:171], v[198:201], v[18:21]
	v_mfma_f32_16x16x32_bf16 v[6:9], v[150:153], v[206:209], v[6:9]
	v_mfma_f32_16x16x32_bf16 v[2:5], v[168:171], v[206:209], v[2:5]
	s_setprio 0
	s_add_i32 s51, s51, 2
	s_add_u32 s49, s49, 0x100
	s_addc_u32 s50, s50, 0
	s_cmp_gt_u32 s51, 41
	s_mov_b64 s[8:9], s[10:11]
	s_barrier
	s_cbranch_scc0 .LBB0_504
	s_and_b64 vcc, exec, s[18:19]
	s_cbranch_vccz .LBB0_507
	s_barrier
